# ctx split-K epilogues (w_o, ffn_down): x base pointer loaded once per item instead of one scalar load round trip per accumulator element
# speedup vs baseline: 1.0078x; 1.0012x over previous
.LBB0_688:
	s_and_b32 s0, s76, 0x300
	s_lshr_b32 s4, s54, 5
	s_lshl_b32 s0, s0, 1
	s_add_u32 s2, s42, s0
	s_addc_u32 s3, s43, 0
	v_mov_b32_e32 v12, v190
	s_mulk_i32 s4, 0x2100
	s_add_u32 s6, s58, s0
	s_addc_u32 s7, s59, 0
	v_ashrrev_i32_e32 v8, 3, v12
	v_lshrrev_b32_e32 v0, 4, v12
	s_and_b32 s0, s90, 0x380
	v_xor_b32_e32 v13, v0, v12
	v_add_u32_e32 v14, s4, v8
	v_add_u32_e32 v2, 64, v14
	v_mov_b64_e32 v[0:1], s[2:3]
	v_add_u32_e32 v4, 0x80, v14
	v_add_u32_e32 v6, 0xc0, v14
	v_add_u32_e32 v15, s0, v8
	v_mov_b64_e32 v[8:9], s[6:7]
	v_lshlrev_b32_e32 v13, 4, v13
	v_mad_i64_i32 v[2:3], s[2:3], v2, s78, v[0:1]
	v_mad_i64_i32 v[4:5], s[2:3], v4, s78, v[0:1]
	v_mad_i64_i32 v[6:7], s[2:3], v6, s78, v[0:1]
	v_mad_i64_i32 v[10:11], s[2:3], v15, s78, v[8:9]
	v_add_u32_e32 v15, 64, v15
	v_mad_i64_i32 v[0:1], s[2:3], v14, s78, v[0:1]
	v_and_b32_e32 v176, 0x70, v13
	v_mad_i64_i32 v[8:9], s[2:3], v15, s78, v[8:9]
	v_lshrrev_b32_e32 v15, 5, v12
	v_lshl_add_u64 v[74:75], v[0:1], 0, v[176:177]
	v_lshrrev_b32_e32 v0, 1, v12
	v_lshlrev_b32_e32 v1, 7, v12
	v_xor_b32_e32 v0, v15, v0
	v_lshl_add_u64 v[72:73], v[2:3], 0, v[176:177]
	v_and_b32_e32 v1, 0xf80, v1
	v_lshlrev_b32_e32 v0, 4, v0
	v_lshlrev_b32_e32 v2, 3, v12
	v_and_b32_e32 v0, 16, v0
	v_and_or_b32 v1, v2, s81, v1
	v_or_b32_e32 v87, v1, v0
	v_bitop3_b32 v79, v1, 32, v0 bitop3:0x36
	v_bitop3_b32 v78, v1, 64, v0 bitop3:0x36
	v_bitop3_b32 v77, v1, s81, v0 bitop3:0x36
	v_ashrrev_i32_e32 v0, 1, v12
	v_lshl_add_u32 v2, v12, 4, 0
	v_and_b32_e32 v86, 0xffffffc0, v0
	v_readfirstlane_b32 s7, v2
	v_add_u32_e32 v0, 0x2000, v2
	s_mov_b32 m0, s7
	v_readfirstlane_b32 s1, v0
	v_add_u32_e32 v0, 0x4000, v2
	global_load_lds_dwordx4 v[74:75], off
	s_mov_b32 m0, s1
	v_readfirstlane_b32 s3, v0
	v_add_u32_e32 v0, 0x6000, v2
	v_lshl_add_u64 v[70:71], v[4:5], 0, v[176:177]
	global_load_lds_dwordx4 v[72:73], off
	s_mov_b32 m0, s3
	v_readfirstlane_b32 s2, v0
	v_add_u32_e32 v0, 0x8000, v2
	v_lshl_add_u64 v[68:69], v[6:7], 0, v[176:177]
	global_load_lds_dwordx4 v[70:71], off
	s_mov_b32 m0, s2
	v_readfirstlane_b32 s6, v0
	v_add_u32_e32 v0, 0xa000, v2
	v_lshl_add_u64 v[66:67], v[10:11], 0, v[176:177]
	global_load_lds_dwordx4 v[68:69], off
	s_mov_b32 m0, s6
	v_readfirstlane_b32 s5, v0
	v_add_u32_e32 v3, 0xc000, v2
	v_lshl_add_u64 v[64:65], v[8:9], 0, v[176:177]
	global_load_lds_dwordx4 v[66:67], off
	s_mov_b32 m0, s5
	v_readfirstlane_b32 s8, v3
	v_add_u32_e32 v3, 0xe000, v2
	global_load_lds_dwordx4 v[64:65], off
	v_lshl_add_u64 v[0:1], v[74:75], 0, s[66:67]
	s_mov_b32 m0, s8
	v_readfirstlane_b32 s8, v3
	v_add_u32_e32 v3, 0x10000, v2
	global_load_lds_dwordx4 v[0:1], off
	v_lshl_add_u64 v[0:1], v[72:73], 0, s[66:67]
	s_mov_b32 m0, s8
	v_readfirstlane_b32 s8, v3
	v_add_u32_e32 v3, 0x12000, v2
	global_load_lds_dwordx4 v[0:1], off
	v_lshl_add_u64 v[0:1], v[70:71], 0, s[66:67]
	s_mov_b32 m0, s8
	v_readfirstlane_b32 s8, v3
	v_add_u32_e32 v3, 0x14000, v2
	global_load_lds_dwordx4 v[0:1], off
	v_lshl_add_u64 v[0:1], v[68:69], 0, s[66:67]
	s_mov_b32 m0, s8
	v_readfirstlane_b32 s8, v3
	v_add_u32_e32 v3, 0x16000, v2
	global_load_lds_dwordx4 v[0:1], off
	v_lshl_add_u64 v[0:1], v[66:67], 0, s[66:67]
	s_mov_b32 m0, s8
	v_readfirstlane_b32 s8, v3
	v_add_u32_e32 v3, 0x18000, v2
	global_load_lds_dwordx4 v[0:1], off
	v_lshl_add_u64 v[0:1], v[64:65], 0, s[66:67]
	s_mov_b32 m0, s8
	v_readfirstlane_b32 s8, v3
	v_add_u32_e32 v3, 0x1a000, v2
	global_load_lds_dwordx4 v[0:1], off
	v_lshl_add_u64 v[0:1], v[74:75], 0, s[70:71]
	s_mov_b32 m0, s8
	v_readfirstlane_b32 s8, v3
	v_add_u32_e32 v3, 0x1c000, v2
	s_waitcnt vmcnt(6)
	s_barrier
	global_load_lds_dwordx4 v[0:1], off
	v_lshl_add_u64 v[0:1], v[72:73], 0, s[70:71]
	s_mov_b32 m0, s8
	v_readfirstlane_b32 s8, v3
	v_add_u32_e32 v3, 0x1e000, v2
	global_load_lds_dwordx4 v[0:1], off
	v_lshl_add_u64 v[0:1], v[70:71], 0, s[70:71]
	s_mov_b32 m0, s8
	v_readfirstlane_b32 s8, v3
	v_add_u32_e32 v3, 0x20000, v2
	global_load_lds_dwordx4 v[0:1], off
	v_lshl_add_u64 v[0:1], v[68:69], 0, s[70:71]
	s_mov_b32 m0, s8
	v_readfirstlane_b32 s8, v3
	v_add_u32_e32 v2, 0x22000, v2
	global_load_lds_dwordx4 v[0:1], off
	v_lshl_add_u64 v[0:1], v[66:67], 0, s[70:71]
	s_mov_b32 m0, s8
	v_readfirstlane_b32 s8, v2
	global_load_lds_dwordx4 v[0:1], off
	v_lshl_add_u64 v[0:1], v[64:65], 0, s[70:71]
	s_mov_b32 m0, s8
	v_and_b32_e32 v76, 64, v12
	global_load_lds_dwordx4 v[0:1], off
	v_lshlrev_b32_e32 v116, 7, v86
	v_lshlrev_b32_e32 v117, 7, v76
	v_add_u32_e32 v118, 0, v116
	v_add_u32_e32 v120, 0, v117
	v_add_u32_e32 v119, v118, v87
	v_add_u32_e32 v121, v120, v87
	v_add_u32_e32 v122, v118, v79
	v_add_u32_e32 v123, v120, v79
	ds_read_b128 v[0:3], v119
	ds_read_b128 v[4:7], v121 offset:32768
	ds_read_b128 v[8:11], v119 offset:4096
	ds_read_b128 v[12:15], v121 offset:36864
	ds_read_b128 v[80:83], v122
	ds_read_b128 v[88:91], v123 offset:32768
	ds_read_b128 v[92:95], v122 offset:4096
	ds_read_b128 v[96:99], v123 offset:36864
	s_waitcnt lgkmcnt(0)
	v_mfma_f32_32x32x16_bf16 v[48:63], v[0:3], v[4:7], 0
	v_add_u32_e32 v124, v118, v78
	v_add_u32_e32 v125, v120, v78
	ds_read_b128 v[100:103], v124
	ds_read_b128 v[104:107], v125 offset:32768
	ds_read_b128 v[108:111], v124 offset:4096
	ds_read_b128 v[112:115], v125 offset:36864
	v_mfma_f32_32x32x16_bf16 v[32:47], v[0:3], v[12:15], 0
	v_mfma_f32_32x32x16_bf16 v[16:31], v[8:11], v[4:7], 0
	v_mfma_f32_32x32x16_bf16 v[0:15], v[8:11], v[12:15], 0
	v_mfma_f32_32x32x16_bf16 v[48:63], v[80:83], v[88:91], v[48:63]
	v_add_u32_e32 v118, v118, v77
	v_add_u32_e32 v126, v120, v77
	v_mfma_f32_32x32x16_bf16 v[32:47], v[80:83], v[96:99], v[32:47]
	ds_read_b128 v[80:83], v118
	v_mfma_f32_32x32x16_bf16 v[16:31], v[92:95], v[88:91], v[16:31]
	v_mfma_f32_32x32x16_bf16 v[0:15], v[92:95], v[96:99], v[0:15]
	ds_read_b128 v[88:91], v126 offset:32768
	ds_read_b128 v[92:95], v118 offset:4096
	ds_read_b128 v[96:99], v126 offset:36864
	s_mov_b32 m0, s7
	v_lshl_add_u64 v[74:75], v[74:75], 0, s[72:73]
	s_waitcnt vmcnt(6)
	s_barrier
	global_load_lds_dwordx4 v[74:75], off
	v_lshl_add_u64 v[72:73], v[72:73], 0, s[72:73]
	s_mov_b32 m0, s1
	v_lshl_add_u64 v[70:71], v[70:71], 0, s[72:73]
	global_load_lds_dwordx4 v[72:73], off
	s_mov_b32 m0, s3
	v_lshl_add_u64 v[68:69], v[68:69], 0, s[72:73]
	global_load_lds_dwordx4 v[70:71], off
	s_mov_b32 m0, s2
	v_lshl_add_u64 v[66:67], v[66:67], 0, s[72:73]
	global_load_lds_dwordx4 v[68:69], off
	s_mov_b32 m0, s6
	v_lshl_add_u64 v[64:65], v[64:65], 0, s[72:73]
	global_load_lds_dwordx4 v[66:67], off
	s_mov_b32 m0, s5
	s_waitcnt lgkmcnt(0)
	v_mfma_f32_32x32x16_bf16 v[48:63], v[100:103], v[104:107], v[48:63]
	global_load_lds_dwordx4 v[64:65], off
	v_mfma_f32_32x32x16_bf16 v[32:47], v[100:103], v[112:115], v[32:47]
	v_mfma_f32_32x32x16_bf16 v[16:31], v[108:111], v[104:107], v[16:31]
	v_mfma_f32_32x32x16_bf16 v[0:15], v[108:111], v[112:115], v[0:15]
	v_add_u32_e32 v112, 0xc000, v120
	v_add_u32_e32 v108, v112, v79
	v_mfma_f32_32x32x16_bf16 v[48:63], v[80:83], v[88:91], v[48:63]
	v_mfma_f32_32x32x16_bf16 v[32:47], v[80:83], v[96:99], v[32:47]
	v_add_u32_e32 v80, v112, v87
	ds_read_b128 v[64:67], v119 offset:49152
	ds_read_b128 v[68:71], v119 offset:53248
	ds_read_b128 v[72:75], v80 offset:32768
	ds_read_b128 v[80:83], v80 offset:36864
	v_mfma_f32_32x32x16_bf16 v[16:31], v[92:95], v[88:91], v[16:31]
	ds_read_b128 v[88:91], v122 offset:49152
	ds_read_b128 v[100:103], v122 offset:53248
	ds_read_b128 v[104:107], v108 offset:32768
	ds_read_b128 v[108:111], v108 offset:36864
	v_mfma_f32_32x32x16_bf16 v[0:15], v[92:95], v[96:99], v[0:15]
	s_waitcnt lgkmcnt(0)
	v_mfma_f32_32x32x16_bf16 v[48:63], v[64:67], v[72:75], v[48:63]
	v_mfma_f32_32x32x16_bf16 v[32:47], v[64:67], v[80:83], v[32:47]
	ds_read_b128 v[64:67], v124 offset:49152
	v_mfma_f32_32x32x16_bf16 v[16:31], v[68:71], v[72:75], v[16:31]
	v_mfma_f32_32x32x16_bf16 v[0:15], v[68:71], v[80:83], v[0:15]
	v_add_u32_e32 v80, v112, v78
	ds_read_b128 v[68:71], v80 offset:32768
	ds_read_b128 v[72:75], v124 offset:53248
	ds_read_b128 v[80:83], v80 offset:36864
	v_mfma_f32_32x32x16_bf16 v[48:63], v[88:91], v[104:107], v[48:63]
	v_mfma_f32_32x32x16_bf16 v[32:47], v[88:91], v[108:111], v[32:47]
	ds_read_b128 v[88:91], v118 offset:49152
	v_mfma_f32_32x32x16_bf16 v[16:31], v[100:103], v[104:107], v[16:31]
	v_mfma_f32_32x32x16_bf16 v[0:15], v[100:103], v[108:111], v[0:15]
	v_add_u32_e32 v100, v112, v77
	ds_read_b128 v[92:95], v100 offset:32768
	ds_read_b128 v[96:99], v118 offset:53248
	ds_read_b128 v[100:103], v100 offset:36864
	s_waitcnt lgkmcnt(0)
	v_mfma_f32_32x32x16_bf16 v[48:63], v[64:67], v[68:71], v[48:63]
	s_add_i32 s1, 0, 0x18000
	v_add_u32_e32 v104, s1, v116
	v_add_u32_e32 v105, s1, v117
	s_waitcnt vmcnt(6)
	s_barrier
	v_mfma_f32_32x32x16_bf16 v[32:47], v[64:67], v[80:83], v[32:47]
	v_mfma_f32_32x32x16_bf16 v[16:31], v[72:75], v[68:71], v[16:31]
	v_mfma_f32_32x32x16_bf16 v[0:15], v[72:75], v[80:83], v[0:15]
	v_add_u32_e32 v72, v104, v87
	v_add_u32_e32 v80, v105, v87
	v_add_u32_e32 v87, v104, v79
	v_add_u32_e32 v79, v105, v79
	ds_read_b128 v[64:67], v72
	ds_read_b128 v[68:71], v80 offset:32768
	ds_read_b128 v[72:75], v72 offset:4096
	ds_read_b128 v[80:83], v80 offset:36864
	v_mfma_f32_32x32x16_bf16 v[48:63], v[88:91], v[92:95], v[48:63]
	v_mfma_f32_32x32x16_bf16 v[32:47], v[88:91], v[100:103], v[32:47]
	ds_read_b128 v[88:91], v87
	v_mfma_f32_32x32x16_bf16 v[16:31], v[96:99], v[92:95], v[16:31]
	v_mfma_f32_32x32x16_bf16 v[0:15], v[96:99], v[100:103], v[0:15]
	ds_read_b128 v[92:95], v79 offset:32768
	ds_read_b128 v[96:99], v87 offset:4096
	ds_read_b128 v[100:103], v79 offset:36864
	s_waitcnt lgkmcnt(0)
	v_mfma_f32_32x32x16_bf16 v[48:63], v[64:67], v[68:71], v[48:63]
	v_mfma_f32_32x32x16_bf16 v[32:47], v[64:67], v[80:83], v[32:47]
	v_mfma_f32_32x32x16_bf16 v[16:31], v[72:75], v[68:71], v[16:31]
	v_mfma_f32_32x32x16_bf16 v[0:15], v[72:75], v[80:83], v[0:15]
	v_add_u32_e32 v72, v104, v78
	v_add_u32_e32 v78, v105, v78
	ds_read_b128 v[64:67], v72
	ds_read_b128 v[68:71], v78 offset:32768
	ds_read_b128 v[72:75], v72 offset:4096
	ds_read_b128 v[78:81], v78 offset:36864
	v_mfma_f32_32x32x16_bf16 v[48:63], v[88:91], v[92:95], v[48:63]
	v_add_u32_e32 v82, v104, v77
	v_add_u32_e32 v77, v105, v77
	v_mfma_f32_32x32x16_bf16 v[32:47], v[88:91], v[100:103], v[32:47]
	ds_read_b128 v[88:91], v82
	v_mfma_f32_32x32x16_bf16 v[16:31], v[96:99], v[92:95], v[16:31]
	v_mfma_f32_32x32x16_bf16 v[0:15], v[96:99], v[100:103], v[0:15]
	ds_read_b128 v[92:95], v77 offset:32768
	ds_read_b128 v[96:99], v82 offset:4096
	ds_read_b128 v[100:103], v77 offset:36864
	s_waitcnt lgkmcnt(0)
	v_mfma_f32_32x32x16_bf16 v[48:63], v[64:67], v[68:71], v[48:63]
	s_waitcnt vmcnt(0)
	s_barrier
	v_mfma_f32_32x32x16_bf16 v[32:47], v[64:67], v[78:81], v[32:47]
	v_mfma_f32_32x32x16_bf16 v[16:31], v[72:75], v[68:71], v[16:31]
	v_mfma_f32_32x32x16_bf16 v[0:15], v[72:75], v[78:81], v[0:15]
	v_mfma_f32_32x32x16_bf16 v[48:63], v[88:91], v[92:95], v[48:63]
	v_mfma_f32_32x32x16_bf16 v[32:47], v[88:91], v[100:103], v[32:47]
	v_mfma_f32_32x32x16_bf16 v[16:31], v[96:99], v[92:95], v[16:31]
	v_mfma_f32_32x32x16_bf16 v[0:15], v[96:99], v[100:103], v[0:15]
	ds_read_b128 v[64:67], v119
	ds_read_b128 v[68:71], v121 offset:32768
	ds_read_b128 v[72:75], v119 offset:4096
	ds_read_b128 v[78:81], v121 offset:36864
	ds_read_b128 v[88:91], v122
	ds_read_b128 v[92:95], v123 offset:32768
	ds_read_b128 v[96:99], v122 offset:4096
	ds_read_b128 v[100:103], v123 offset:36864
	s_waitcnt lgkmcnt(0)
	v_mfma_f32_32x32x16_bf16 v[48:63], v[64:67], v[68:71], v[48:63]
	v_mfma_f32_32x32x16_bf16 v[32:47], v[64:67], v[78:81], v[32:47]
	v_mfma_f32_32x32x16_bf16 v[16:31], v[72:75], v[68:71], v[16:31]
	v_mfma_f32_32x32x16_bf16 v[0:15], v[72:75], v[78:81], v[0:15]
	ds_read_b128 v[64:67], v124
	ds_read_b128 v[68:71], v125 offset:32768
	ds_read_b128 v[72:75], v124 offset:4096
	ds_read_b128 v[78:81], v125 offset:36864
	v_mfma_f32_32x32x16_bf16 v[48:63], v[88:91], v[92:95], v[48:63]
	v_mfma_f32_32x32x16_bf16 v[32:47], v[88:91], v[100:103], v[32:47]
	v_mfma_f32_32x32x16_bf16 v[16:31], v[96:99], v[92:95], v[16:31]
	v_mfma_f32_32x32x16_bf16 v[0:15], v[96:99], v[100:103], v[0:15]
	ds_read_b128 v[88:91], v118
	ds_read_b128 v[92:95], v126 offset:32768
	ds_read_b128 v[96:99], v118 offset:4096
	ds_read_b128 v[100:103], v126 offset:36864
	s_waitcnt lgkmcnt(0)
	v_mfma_f32_32x32x16_bf16 v[48:63], v[64:67], v[68:71], v[48:63]
	s_waitcnt vmcnt(0)
	s_barrier
	v_mfma_f32_32x32x16_bf16 v[32:47], v[64:67], v[78:81], v[32:47]
	v_or3_b32 v64, s0, v84, v76
	v_lshlrev_b32_e32 v176, 2, v64
	global_load_dword v65, v176, s[62:63]
	v_add_u32_e32 v64, s4, v86
	v_or_b32_e32 v64, v64, v85
	v_mul_hi_i32 v66, v64, s35
	v_lshrrev_b32_e32 v67, 31, v66
	v_mfma_f32_32x32x16_bf16 v[16:31], v[72:75], v[68:71], v[16:31]
	v_ashrrev_i32_e32 v66, 11, v66
	v_add_u32_e32 v67, v66, v67
	v_mad_i32_i24 v70, v67, s33, v64
	v_lshlrev_b32_e32 v68, 13, v67
	v_cmp_lt_i32_e32 vcc, s82, v70
	v_add3_u32 v64, v68, v70, s79
	v_mfma_f32_32x32x16_bf16 v[0:15], v[72:75], v[78:81], v[0:15]
	v_mfma_f32_32x32x16_bf16 v[48:63], v[88:91], v[92:95], v[48:63]
	v_mfma_f32_32x32x16_bf16 v[32:47], v[88:91], v[100:103], v[32:47]
	v_mfma_f32_32x32x16_bf16 v[16:31], v[96:99], v[92:95], v[16:31]
	v_mfma_f32_32x32x16_bf16 v[0:15], v[96:99], v[100:103], v[0:15]
	s_load_dwordx2 s[92:93], s[40:41], 0xe8
	s_waitcnt lgkmcnt(0)
	s_and_saveexec_b64 s[0:1], vcc
	s_xor_b64 s[0:1], exec, s[0:1]
	s_mov_b64 s[2:3], s[92:93]
	v_add3_u32 v66, v68, v70, s79
	s_or_saveexec_b64 s[0:1], s[0:1]
	s_waitcnt lgkmcnt(0)
	v_mov_b64_e32 v[68:69], s[2:3]
	v_lshl_add_u32 v88, v67, 8, v70
	s_xor_b64 exec, exec, s[0:1]
	v_lshl_add_u32 v66, v67, 8, v70
	v_mov_b64_e32 v[68:69], s[64:65]
	s_or_b64 exec, exec, s[0:1]
	v_ashrrev_i32_e32 v67, 31, v66
	v_lshlrev_b64 v[66:67], 12, v[66:67]
	v_lshl_add_u64 v[66:67], v[68:69], 0, v[66:67]
	v_lshl_add_u64 v[66:67], v[66:67], 0, v[176:177]
	s_waitcnt vmcnt(0)
	v_mul_f32_e32 v48, v48, v65
	global_atomic_add_f32 v[66:67], v48, off
	v_or_b32_e32 v87, s4, v85
	v_add3_u32 v66, v86, v87, 1
	v_mul_hi_i32 v48, v66, s35
	v_lshrrev_b32_e32 v67, 31, v48
	v_ashrrev_i32_e32 v48, 11, v48
	v_add_u32_e32 v48, v48, v67
	v_mad_i32_i24 v69, v48, s33, v66
	v_lshlrev_b32_e32 v67, 13, v48
	v_cmp_lt_i32_e64 s[2:3], s82, v69
	v_add3_u32 v66, v67, v69, s79
	s_and_saveexec_b64 s[0:1], s[2:3]
	s_xor_b64 s[0:1], exec, s[0:1]
	s_mov_b64 s[4:5], s[92:93]
	v_add3_u32 v68, v67, v69, s79
	s_or_saveexec_b64 s[0:1], s[0:1]
	s_waitcnt lgkmcnt(0)
	v_mov_b64_e32 v[70:71], s[4:5]
	v_lshl_add_u32 v67, v48, 8, v69
	s_xor_b64 exec, exec, s[0:1]
	v_lshl_add_u32 v68, v48, 8, v69
	v_mov_b64_e32 v[70:71], s[64:65]
	s_or_b64 exec, exec, s[0:1]
	v_ashrrev_i32_e32 v69, 31, v68
	v_lshlrev_b64 v[68:69], 12, v[68:69]
	v_lshl_add_u64 v[68:69], v[70:71], 0, v[68:69]
	v_lshl_add_u64 v[68:69], v[68:69], 0, v[176:177]
	v_mul_f32_e32 v48, v49, v65
	global_atomic_add_f32 v[68:69], v48, off
	v_add3_u32 v48, v86, v87, 2
	v_mul_hi_i32 v49, v48, s35
	v_lshrrev_b32_e32 v68, 31, v49
	v_ashrrev_i32_e32 v49, 11, v49
	v_add_u32_e32 v49, v49, v68
	v_mad_i32_i24 v72, v49, s33, v48
	v_lshlrev_b32_e32 v69, 13, v49
	v_cmp_lt_i32_e64 s[4:5], s82, v72
	v_add3_u32 v68, v69, v72, s79
	s_and_saveexec_b64 s[0:1], s[4:5]
	s_xor_b64 s[0:1], exec, s[0:1]
	s_mov_b64 s[6:7], s[92:93]
	v_add3_u32 v48, v69, v72, s79
	s_or_saveexec_b64 s[0:1], s[0:1]
	s_waitcnt lgkmcnt(0)
	v_mov_b64_e32 v[70:71], s[6:7]
	v_lshl_add_u32 v69, v49, 8, v72
	s_xor_b64 exec, exec, s[0:1]
	v_lshl_add_u32 v48, v49, 8, v72
	v_mov_b64_e32 v[70:71], s[64:65]
	s_or_b64 exec, exec, s[0:1]
	v_ashrrev_i32_e32 v49, 31, v48
	v_lshlrev_b64 v[48:49], 12, v[48:49]
	v_lshl_add_u64 v[48:49], v[70:71], 0, v[48:49]
	v_lshl_add_u64 v[48:49], v[48:49], 0, v[176:177]
	v_mul_f32_e32 v50, v50, v65
	global_atomic_add_f32 v[48:49], v50, off
	v_add3_u32 v48, v86, v87, 3
	v_mul_hi_i32 v49, v48, s35
	v_lshrrev_b32_e32 v50, 31, v49
	v_ashrrev_i32_e32 v49, 11, v49
	v_add_u32_e32 v49, v49, v50
	v_mad_i32_i24 v72, v49, s33, v48
	v_lshlrev_b32_e32 v70, 13, v49
	v_cmp_lt_i32_e64 s[6:7], s82, v72
	v_add3_u32 v50, v70, v72, s79
	s_and_saveexec_b64 s[0:1], s[6:7]
	s_xor_b64 s[0:1], exec, s[0:1]
	s_mov_b64 s[8:9], s[92:93]
	v_add3_u32 v48, v70, v72, s79
	s_or_saveexec_b64 s[0:1], s[0:1]
	s_waitcnt lgkmcnt(0)
	v_mov_b64_e32 v[70:71], s[8:9]
	v_lshl_add_u32 v89, v49, 8, v72
	s_xor_b64 exec, exec, s[0:1]
	v_lshl_add_u32 v48, v49, 8, v72
	v_mov_b64_e32 v[70:71], s[64:65]
	s_or_b64 exec, exec, s[0:1]
	v_ashrrev_i32_e32 v49, 31, v48
	v_lshlrev_b64 v[48:49], 12, v[48:49]
	v_lshl_add_u64 v[48:49], v[70:71], 0, v[48:49]
	v_lshl_add_u64 v[48:49], v[48:49], 0, v[176:177]
	v_mul_f32_e32 v51, v51, v65
	global_atomic_add_f32 v[48:49], v51, off
	v_add3_u32 v48, v86, v87, 8
	v_mul_hi_i32 v49, v48, s35
	v_lshrrev_b32_e32 v51, 31, v49
	v_ashrrev_i32_e32 v49, 11, v49
	v_add_u32_e32 v49, v49, v51
	v_mad_i32_i24 v51, v49, s33, v48
	v_lshlrev_b32_e32 v71, 13, v49
	v_cmp_lt_i32_e64 s[8:9], s82, v51
	v_add3_u32 v70, v71, v51, s79
	s_and_saveexec_b64 s[0:1], s[8:9]
	s_xor_b64 s[0:1], exec, s[0:1]
	s_mov_b64 s[10:11], s[92:93]
	v_add3_u32 v48, v71, v51, s79
	s_or_saveexec_b64 s[0:1], s[0:1]
	s_waitcnt lgkmcnt(0)
	v_mov_b64_e32 v[72:73], s[10:11]
	v_lshl_add_u32 v71, v49, 8, v51
	s_xor_b64 exec, exec, s[0:1]
	v_lshl_add_u32 v48, v49, 8, v51
	v_mov_b64_e32 v[72:73], s[64:65]
	s_or_b64 exec, exec, s[0:1]
	v_ashrrev_i32_e32 v49, 31, v48
	v_lshlrev_b64 v[48:49], 12, v[48:49]
	v_lshl_add_u64 v[48:49], v[72:73], 0, v[48:49]
	v_lshl_add_u64 v[48:49], v[48:49], 0, v[176:177]
	v_mul_f32_e32 v51, v52, v65
	global_atomic_add_f32 v[48:49], v51, off
	v_add3_u32 v48, v86, v87, 9
	v_mul_hi_i32 v49, v48, s35
	v_lshrrev_b32_e32 v51, 31, v49
	v_ashrrev_i32_e32 v49, 11, v49
	v_add_u32_e32 v49, v49, v51
	v_mad_i32_i24 v51, v49, s33, v48
	v_lshlrev_b32_e32 v72, 13, v49
	v_cmp_lt_i32_e64 s[10:11], s82, v51
	v_add3_u32 v52, v72, v51, s79
	s_and_saveexec_b64 s[0:1], s[10:11]
	s_xor_b64 s[0:1], exec, s[0:1]
	s_mov_b64 s[12:13], s[92:93]
	v_add3_u32 v48, v72, v51, s79
	s_or_saveexec_b64 s[0:1], s[0:1]
	s_waitcnt lgkmcnt(0)
	v_mov_b64_e32 v[72:73], s[12:13]
	v_lshl_add_u32 v90, v49, 8, v51
	s_xor_b64 exec, exec, s[0:1]
	v_lshl_add_u32 v48, v49, 8, v51
	v_mov_b64_e32 v[72:73], s[64:65]
	s_or_b64 exec, exec, s[0:1]
	v_ashrrev_i32_e32 v49, 31, v48
	v_lshlrev_b64 v[48:49], 12, v[48:49]
	v_lshl_add_u64 v[48:49], v[72:73], 0, v[48:49]
	v_lshl_add_u64 v[48:49], v[48:49], 0, v[176:177]
	v_mul_f32_e32 v51, v53, v65
	global_atomic_add_f32 v[48:49], v51, off
	v_add3_u32 v48, v86, v87, 10
	v_mul_hi_i32 v49, v48, s35
	v_lshrrev_b32_e32 v51, 31, v49
	v_ashrrev_i32_e32 v49, 11, v49
	v_add_u32_e32 v49, v49, v51
	v_mad_i32_i24 v51, v49, s33, v48
	v_lshlrev_b32_e32 v53, 13, v49
	v_cmp_lt_i32_e64 s[12:13], s82, v51
	v_add3_u32 v72, v53, v51, s79
	s_and_saveexec_b64 s[0:1], s[12:13]
	s_xor_b64 s[0:1], exec, s[0:1]
	s_mov_b64 s[14:15], s[92:93]
	v_add3_u32 v48, v53, v51, s79
	s_or_saveexec_b64 s[0:1], s[0:1]
	s_waitcnt lgkmcnt(0)
	v_mov_b64_e32 v[74:75], s[14:15]
	v_lshl_add_u32 v73, v49, 8, v51
	s_xor_b64 exec, exec, s[0:1]
	v_lshl_add_u32 v48, v49, 8, v51
	v_mov_b64_e32 v[74:75], s[64:65]
	s_or_b64 exec, exec, s[0:1]
	v_ashrrev_i32_e32 v49, 31, v48
	v_lshlrev_b64 v[48:49], 12, v[48:49]
	v_lshl_add_u64 v[48:49], v[74:75], 0, v[48:49]
	v_lshl_add_u64 v[48:49], v[48:49], 0, v[176:177]
	v_mul_f32_e32 v51, v54, v65
	global_atomic_add_f32 v[48:49], v51, off
	v_add3_u32 v48, v86, v87, 11
	v_mul_hi_i32 v49, v48, s35
	v_lshrrev_b32_e32 v51, 31, v49
	v_ashrrev_i32_e32 v49, 11, v49
	v_add_u32_e32 v49, v49, v51
	v_mad_i32_i24 v51, v49, s33, v48
	v_lshlrev_b32_e32 v53, 13, v49
	v_cmp_lt_i32_e64 s[14:15], s82, v51
	v_add3_u32 v54, v53, v51, s79
	s_and_saveexec_b64 s[0:1], s[14:15]
	s_xor_b64 s[0:1], exec, s[0:1]
	s_mov_b64 s[16:17], s[92:93]
	v_add3_u32 v48, v53, v51, s79
	s_or_saveexec_b64 s[0:1], s[0:1]
	s_waitcnt lgkmcnt(0)
	v_mov_b64_e32 v[74:75], s[16:17]
	v_lshl_add_u32 v91, v49, 8, v51
	s_xor_b64 exec, exec, s[0:1]
	v_lshl_add_u32 v48, v49, 8, v51
	v_mov_b64_e32 v[74:75], s[64:65]
	s_or_b64 exec, exec, s[0:1]
	v_ashrrev_i32_e32 v49, 31, v48
	v_lshlrev_b64 v[48:49], 12, v[48:49]
	v_lshl_add_u64 v[48:49], v[74:75], 0, v[48:49]
	v_lshl_add_u64 v[48:49], v[48:49], 0, v[176:177]
	v_mul_f32_e32 v51, v55, v65
	global_atomic_add_f32 v[48:49], v51, off
	v_add3_u32 v48, v86, v87, 16
	v_mul_hi_i32 v49, v48, s35
	v_lshrrev_b32_e32 v51, 31, v49
	v_ashrrev_i32_e32 v49, 11, v49
	v_add_u32_e32 v49, v49, v51
	v_mad_i32_i24 v51, v49, s33, v48
	v_lshlrev_b32_e32 v53, 13, v49
	v_cmp_lt_i32_e64 s[16:17], s82, v51
	v_add3_u32 v74, v53, v51, s79
	s_and_saveexec_b64 s[0:1], s[16:17]
	s_xor_b64 s[0:1], exec, s[0:1]
	s_mov_b64 s[18:19], s[92:93]
	v_add3_u32 v48, v53, v51, s79
	s_or_saveexec_b64 s[0:1], s[0:1]
	s_waitcnt lgkmcnt(0)
	v_mov_b64_e32 v[76:77], s[18:19]
	v_lshl_add_u32 v75, v49, 8, v51
	s_xor_b64 exec, exec, s[0:1]
	v_lshl_add_u32 v48, v49, 8, v51
	v_mov_b64_e32 v[76:77], s[64:65]
	s_or_b64 exec, exec, s[0:1]
	v_ashrrev_i32_e32 v49, 31, v48
	v_lshlrev_b64 v[48:49], 12, v[48:49]
	v_lshl_add_u64 v[48:49], v[76:77], 0, v[48:49]
	v_lshl_add_u64 v[48:49], v[48:49], 0, v[176:177]
	v_mul_f32_e32 v51, v56, v65
	global_atomic_add_f32 v[48:49], v51, off
	v_add3_u32 v48, v86, v87, 17
	v_mul_hi_i32 v49, v48, s35
	v_lshrrev_b32_e32 v51, 31, v49
	v_ashrrev_i32_e32 v49, 11, v49
	v_add_u32_e32 v49, v49, v51
	v_mad_i32_i24 v51, v49, s33, v48
	v_lshlrev_b32_e32 v53, 13, v49
	v_cmp_lt_i32_e64 s[18:19], s82, v51
	v_add3_u32 v56, v53, v51, s79
	s_and_saveexec_b64 s[0:1], s[18:19]
	s_xor_b64 s[0:1], exec, s[0:1]
	s_mov_b64 s[20:21], s[92:93]
	v_add3_u32 v48, v53, v51, s79
	s_or_saveexec_b64 s[0:1], s[0:1]
	s_waitcnt lgkmcnt(0)
	v_mov_b64_e32 v[76:77], s[20:21]
	v_lshl_add_u32 v92, v49, 8, v51
	s_xor_b64 exec, exec, s[0:1]
	v_lshl_add_u32 v48, v49, 8, v51
	v_mov_b64_e32 v[76:77], s[64:65]
	s_or_b64 exec, exec, s[0:1]
	v_ashrrev_i32_e32 v49, 31, v48
	v_lshlrev_b64 v[48:49], 12, v[48:49]
	v_lshl_add_u64 v[48:49], v[76:77], 0, v[48:49]
	v_lshl_add_u64 v[48:49], v[48:49], 0, v[176:177]
	v_mul_f32_e32 v51, v57, v65
	global_atomic_add_f32 v[48:49], v51, off
	v_add3_u32 v48, v86, v87, 18
	v_mul_hi_i32 v49, v48, s35
	v_lshrrev_b32_e32 v51, 31, v49
	v_ashrrev_i32_e32 v49, 11, v49
	v_add_u32_e32 v49, v49, v51
	v_mad_i32_i24 v51, v49, s33, v48
	v_lshlrev_b32_e32 v53, 13, v49
	v_cmp_lt_i32_e64 s[20:21], s82, v51
	v_add3_u32 v76, v53, v51, s79
	s_and_saveexec_b64 s[0:1], s[20:21]
	s_xor_b64 s[0:1], exec, s[0:1]
	s_mov_b64 s[22:23], s[92:93]
	v_add3_u32 v48, v53, v51, s79
	s_or_saveexec_b64 s[0:1], s[0:1]
	s_waitcnt lgkmcnt(0)
	v_mov_b64_e32 v[78:79], s[22:23]
	v_lshl_add_u32 v77, v49, 8, v51
	s_xor_b64 exec, exec, s[0:1]
	v_lshl_add_u32 v48, v49, 8, v51
	v_mov_b64_e32 v[78:79], s[64:65]
	s_or_b64 exec, exec, s[0:1]
	v_ashrrev_i32_e32 v49, 31, v48
	v_lshlrev_b64 v[48:49], 12, v[48:49]
	v_lshl_add_u64 v[48:49], v[78:79], 0, v[48:49]
	v_lshl_add_u64 v[48:49], v[48:49], 0, v[176:177]
	v_mul_f32_e32 v51, v58, v65
	global_atomic_add_f32 v[48:49], v51, off
	v_add3_u32 v48, v86, v87, 19
	v_mul_hi_i32 v49, v48, s35
	v_lshrrev_b32_e32 v51, 31, v49
	v_ashrrev_i32_e32 v49, 11, v49
	v_add_u32_e32 v49, v49, v51
	v_mad_i32_i24 v51, v49, s33, v48
	v_lshlrev_b32_e32 v53, 13, v49
	v_cmp_lt_i32_e64 s[22:23], s82, v51
	v_add3_u32 v58, v53, v51, s79
	s_and_saveexec_b64 s[0:1], s[22:23]
	s_xor_b64 s[0:1], exec, s[0:1]
	s_mov_b64 s[24:25], s[92:93]
	v_add3_u32 v48, v53, v51, s79
	s_or_saveexec_b64 s[0:1], s[0:1]
	s_waitcnt lgkmcnt(0)
	v_mov_b64_e32 v[78:79], s[24:25]
	v_lshl_add_u32 v93, v49, 8, v51
	s_xor_b64 exec, exec, s[0:1]
	v_lshl_add_u32 v48, v49, 8, v51
	v_mov_b64_e32 v[78:79], s[64:65]
	s_or_b64 exec, exec, s[0:1]
	v_ashrrev_i32_e32 v49, 31, v48
	v_lshlrev_b64 v[48:49], 12, v[48:49]
	v_lshl_add_u64 v[48:49], v[78:79], 0, v[48:49]
	v_lshl_add_u64 v[48:49], v[48:49], 0, v[176:177]
	v_mul_f32_e32 v51, v59, v65
	global_atomic_add_f32 v[48:49], v51, off
	v_add3_u32 v48, v86, v87, 24
	v_mul_hi_i32 v49, v48, s35
	v_lshrrev_b32_e32 v51, 31, v49
	v_ashrrev_i32_e32 v49, 11, v49
	v_add_u32_e32 v49, v49, v51
	v_mad_i32_i24 v51, v49, s33, v48
	v_lshlrev_b32_e32 v53, 13, v49
	v_cmp_lt_i32_e64 s[24:25], s82, v51
	v_add3_u32 v78, v53, v51, s79
	s_and_saveexec_b64 s[0:1], s[24:25]
	s_xor_b64 s[0:1], exec, s[0:1]
	s_mov_b64 s[26:27], s[92:93]
	v_add3_u32 v48, v53, v51, s79
	s_or_saveexec_b64 s[0:1], s[0:1]
	s_waitcnt lgkmcnt(0)
	v_mov_b64_e32 v[80:81], s[26:27]
	v_lshl_add_u32 v79, v49, 8, v51
	s_xor_b64 exec, exec, s[0:1]
	v_lshl_add_u32 v48, v49, 8, v51
	v_mov_b64_e32 v[80:81], s[64:65]
	s_or_b64 exec, exec, s[0:1]
	v_ashrrev_i32_e32 v49, 31, v48
	v_lshlrev_b64 v[48:49], 12, v[48:49]
	v_lshl_add_u64 v[48:49], v[80:81], 0, v[48:49]
	v_lshl_add_u64 v[48:49], v[48:49], 0, v[176:177]
	v_mul_f32_e32 v51, v60, v65
	global_atomic_add_f32 v[48:49], v51, off
	v_add3_u32 v48, v86, v87, 25
	v_mul_hi_i32 v49, v48, s35
	v_lshrrev_b32_e32 v51, 31, v49
	v_ashrrev_i32_e32 v49, 11, v49
	v_add_u32_e32 v49, v49, v51
	v_mad_i32_i24 v51, v49, s33, v48
	v_lshlrev_b32_e32 v53, 13, v49
	v_cmp_lt_i32_e64 s[26:27], s82, v51
	v_add3_u32 v60, v53, v51, s79
	s_and_saveexec_b64 s[0:1], s[26:27]
	s_xor_b64 s[0:1], exec, s[0:1]
	s_mov_b64 s[28:29], s[92:93]
	v_add3_u32 v48, v53, v51, s79
	s_or_saveexec_b64 s[0:1], s[0:1]
	s_waitcnt lgkmcnt(0)
	v_mov_b64_e32 v[80:81], s[28:29]
	v_lshl_add_u32 v94, v49, 8, v51
	s_xor_b64 exec, exec, s[0:1]
	v_lshl_add_u32 v48, v49, 8, v51
	v_mov_b64_e32 v[80:81], s[64:65]
	s_or_b64 exec, exec, s[0:1]
	v_ashrrev_i32_e32 v49, 31, v48
	v_lshlrev_b64 v[48:49], 12, v[48:49]
	v_lshl_add_u64 v[48:49], v[80:81], 0, v[48:49]
	v_lshl_add_u64 v[48:49], v[48:49], 0, v[176:177]
	v_mul_f32_e32 v51, v61, v65
	global_atomic_add_f32 v[48:49], v51, off
	v_add3_u32 v48, v86, v87, 26
	v_mul_hi_i32 v49, v48, s35
	v_lshrrev_b32_e32 v51, 31, v49
	v_ashrrev_i32_e32 v49, 11, v49
	v_add_u32_e32 v49, v49, v51
	v_mad_i32_i24 v51, v49, s33, v48
	v_lshlrev_b32_e32 v53, 13, v49
	v_cmp_lt_i32_e64 s[28:29], s82, v51
	v_add3_u32 v80, v53, v51, s79
	s_and_saveexec_b64 s[0:1], s[28:29]
	s_xor_b64 s[0:1], exec, s[0:1]
	s_mov_b64 s[30:31], s[92:93]
	v_add3_u32 v48, v53, v51, s79
	s_or_saveexec_b64 s[0:1], s[0:1]
	s_waitcnt lgkmcnt(0)
	v_mov_b64_e32 v[82:83], s[30:31]
	v_lshl_add_u32 v81, v49, 8, v51
	s_xor_b64 exec, exec, s[0:1]
	v_lshl_add_u32 v48, v49, 8, v51
	v_mov_b64_e32 v[82:83], s[64:65]
	s_or_b64 exec, exec, s[0:1]
	v_ashrrev_i32_e32 v49, 31, v48
	v_lshlrev_b64 v[48:49], 12, v[48:49]
	v_lshl_add_u64 v[48:49], v[82:83], 0, v[48:49]
	v_lshl_add_u64 v[48:49], v[48:49], 0, v[176:177]
	v_mul_f32_e32 v51, v62, v65
	global_atomic_add_f32 v[48:49], v51, off
	v_add3_u32 v48, v86, v87, 27
	v_mul_hi_i32 v49, v48, s35
	v_lshrrev_b32_e32 v51, 31, v49
	v_ashrrev_i32_e32 v49, 11, v49
	v_add_u32_e32 v49, v49, v51
	v_mad_i32_i24 v51, v49, s33, v48
	v_lshlrev_b32_e32 v53, 13, v49
	v_cmp_lt_i32_e64 s[30:31], s82, v51
	v_add3_u32 v62, v53, v51, s79
	s_and_saveexec_b64 s[0:1], s[30:31]
	s_xor_b64 s[0:1], exec, s[0:1]
	s_mov_b64 s[74:75], s[92:93]
	v_add3_u32 v48, v53, v51, s79
	s_or_saveexec_b64 s[0:1], s[0:1]
	s_waitcnt lgkmcnt(0)
	v_mov_b64_e32 v[82:83], s[74:75]
	v_lshl_add_u32 v95, v49, 8, v51
	s_xor_b64 exec, exec, s[0:1]
	v_lshl_add_u32 v48, v49, 8, v51
	v_mov_b64_e32 v[82:83], s[64:65]
	s_or_b64 exec, exec, s[0:1]
	v_ashrrev_i32_e32 v49, 31, v48
	v_lshlrev_b64 v[48:49], 12, v[48:49]
	v_lshl_add_u64 v[48:49], v[82:83], 0, v[48:49]
	v_lshl_add_u64 v[48:49], v[48:49], 0, v[176:177]
	v_mul_f32_e32 v51, v63, v65
	global_atomic_add_f32 v[48:49], v51, off
	v_or_b32_e32 v48, 0x80, v176
	global_load_dword v49, v48, s[62:63]
	s_and_saveexec_b64 s[0:1], vcc
	s_xor_b64 s[0:1], exec, s[0:1]
	s_mov_b64 s[74:75], s[92:93]
	s_or_saveexec_b64 s[0:1], s[0:1]
	s_waitcnt lgkmcnt(0)
	v_mov_b64_e32 v[82:83], s[74:75]
	s_xor_b64 exec, exec, s[0:1]
	v_mov_b64_e32 v[82:83], s[64:65]
	v_mov_b32_e32 v64, v88
	s_or_b64 exec, exec, s[0:1]
	v_ashrrev_i32_e32 v65, 31, v64
	v_lshlrev_b64 v[64:65], 12, v[64:65]
	v_lshl_add_u64 v[64:65], v[82:83], 0, v[64:65]
	v_lshl_add_u64 v[64:65], v[64:65], 0, v[176:177]
	s_waitcnt vmcnt(0)
	v_mul_f32_e32 v32, v32, v49
	global_atomic_add_f32 v[64:65], v32, off offset:128
	s_and_saveexec_b64 s[0:1], s[2:3]
	s_xor_b64 s[0:1], exec, s[0:1]
	s_mov_b64 s[74:75], s[92:93]
	s_or_saveexec_b64 s[0:1], s[0:1]
	s_waitcnt lgkmcnt(0)
	v_mov_b64_e32 v[64:65], s[74:75]
	s_xor_b64 exec, exec, s[0:1]
	v_mov_b64_e32 v[64:65], s[64:65]
	v_mov_b32_e32 v66, v67
	s_or_b64 exec, exec, s[0:1]
	v_ashrrev_i32_e32 v67, 31, v66
	v_lshlrev_b64 v[66:67], 12, v[66:67]
	v_lshl_add_u64 v[64:65], v[64:65], 0, v[66:67]
	v_lshl_add_u64 v[64:65], v[64:65], 0, v[176:177]
	v_mul_f32_e32 v32, v33, v49
	global_atomic_add_f32 v[64:65], v32, off offset:128
	s_and_saveexec_b64 s[0:1], s[4:5]
	s_xor_b64 s[0:1], exec, s[0:1]
	s_mov_b64 s[2:3], s[92:93]
	s_or_saveexec_b64 s[0:1], s[0:1]
	s_waitcnt lgkmcnt(0)
	v_mov_b64_e32 v[32:33], s[2:3]
	s_xor_b64 exec, exec, s[0:1]
	v_mov_b64_e32 v[32:33], s[64:65]
	v_mov_b32_e32 v68, v69
	s_or_b64 exec, exec, s[0:1]
	v_ashrrev_i32_e32 v69, 31, v68
	v_lshlrev_b64 v[64:65], 12, v[68:69]
	v_lshl_add_u64 v[32:33], v[32:33], 0, v[64:65]
	v_lshl_add_u64 v[32:33], v[32:33], 0, v[176:177]
	v_mul_f32_e32 v34, v34, v49
	global_atomic_add_f32 v[32:33], v34, off offset:128
	s_and_saveexec_b64 s[0:1], s[6:7]
	s_xor_b64 s[0:1], exec, s[0:1]
	s_mov_b64 s[2:3], s[92:93]
	s_or_saveexec_b64 s[0:1], s[0:1]
	s_waitcnt lgkmcnt(0)
	v_mov_b64_e32 v[32:33], s[2:3]
	s_xor_b64 exec, exec, s[0:1]
	v_mov_b64_e32 v[32:33], s[64:65]
	v_mov_b32_e32 v50, v89
	s_or_b64 exec, exec, s[0:1]
	v_ashrrev_i32_e32 v51, 31, v50
	v_lshlrev_b64 v[50:51], 12, v[50:51]
	v_lshl_add_u64 v[32:33], v[32:33], 0, v[50:51]
	v_lshl_add_u64 v[32:33], v[32:33], 0, v[176:177]
	v_mul_f32_e32 v34, v35, v49
	global_atomic_add_f32 v[32:33], v34, off offset:128
	s_and_saveexec_b64 s[0:1], s[8:9]
	s_xor_b64 s[0:1], exec, s[0:1]
	s_mov_b64 s[2:3], s[92:93]
	s_or_saveexec_b64 s[0:1], s[0:1]
	s_waitcnt lgkmcnt(0)
	v_mov_b64_e32 v[32:33], s[2:3]
	s_xor_b64 exec, exec, s[0:1]
	v_mov_b64_e32 v[32:33], s[64:65]
	v_mov_b32_e32 v70, v71
	s_or_b64 exec, exec, s[0:1]
	v_ashrrev_i32_e32 v71, 31, v70
	v_lshlrev_b64 v[34:35], 12, v[70:71]
	v_lshl_add_u64 v[32:33], v[32:33], 0, v[34:35]
	v_lshl_add_u64 v[32:33], v[32:33], 0, v[176:177]
	v_mul_f32_e32 v34, v36, v49
	global_atomic_add_f32 v[32:33], v34, off offset:128
	s_and_saveexec_b64 s[0:1], s[10:11]
	s_xor_b64 s[0:1], exec, s[0:1]
	s_mov_b64 s[2:3], s[92:93]
	s_or_saveexec_b64 s[0:1], s[0:1]
	s_waitcnt lgkmcnt(0)
	v_mov_b64_e32 v[32:33], s[2:3]
	s_xor_b64 exec, exec, s[0:1]
	v_mov_b64_e32 v[32:33], s[64:65]
	v_mov_b32_e32 v52, v90
	s_or_b64 exec, exec, s[0:1]
	v_ashrrev_i32_e32 v53, 31, v52
	v_lshlrev_b64 v[34:35], 12, v[52:53]
	v_lshl_add_u64 v[32:33], v[32:33], 0, v[34:35]
	v_lshl_add_u64 v[32:33], v[32:33], 0, v[176:177]
	v_mul_f32_e32 v34, v37, v49
	global_atomic_add_f32 v[32:33], v34, off offset:128
	s_and_saveexec_b64 s[0:1], s[12:13]
	s_xor_b64 s[0:1], exec, s[0:1]
	s_mov_b64 s[2:3], s[92:93]
	s_or_saveexec_b64 s[0:1], s[0:1]
	s_waitcnt lgkmcnt(0)
	v_mov_b64_e32 v[32:33], s[2:3]
	s_xor_b64 exec, exec, s[0:1]
	v_mov_b64_e32 v[32:33], s[64:65]
	v_mov_b32_e32 v72, v73
	s_or_b64 exec, exec, s[0:1]
	v_ashrrev_i32_e32 v73, 31, v72
	v_lshlrev_b64 v[34:35], 12, v[72:73]
	v_lshl_add_u64 v[32:33], v[32:33], 0, v[34:35]
	v_lshl_add_u64 v[32:33], v[32:33], 0, v[176:177]
	v_mul_f32_e32 v34, v38, v49
	global_atomic_add_f32 v[32:33], v34, off offset:128
	s_and_saveexec_b64 s[0:1], s[14:15]
	s_xor_b64 s[0:1], exec, s[0:1]
	s_mov_b64 s[2:3], s[92:93]
	s_or_saveexec_b64 s[0:1], s[0:1]
	s_waitcnt lgkmcnt(0)
	v_mov_b64_e32 v[32:33], s[2:3]
	s_xor_b64 exec, exec, s[0:1]
	v_mov_b64_e32 v[32:33], s[64:65]
	v_mov_b32_e32 v54, v91
	s_or_b64 exec, exec, s[0:1]
	v_ashrrev_i32_e32 v55, 31, v54
	v_lshlrev_b64 v[34:35], 12, v[54:55]
	v_lshl_add_u64 v[32:33], v[32:33], 0, v[34:35]
	v_lshl_add_u64 v[32:33], v[32:33], 0, v[176:177]
	v_mul_f32_e32 v34, v39, v49
	global_atomic_add_f32 v[32:33], v34, off offset:128
	s_and_saveexec_b64 s[0:1], s[16:17]
	s_xor_b64 s[0:1], exec, s[0:1]
	s_mov_b64 s[2:3], s[92:93]
	s_or_saveexec_b64 s[0:1], s[0:1]
	s_waitcnt lgkmcnt(0)
	v_mov_b64_e32 v[32:33], s[2:3]
	s_xor_b64 exec, exec, s[0:1]
	v_mov_b64_e32 v[32:33], s[64:65]
	v_mov_b32_e32 v74, v75
	s_or_b64 exec, exec, s[0:1]
	v_ashrrev_i32_e32 v75, 31, v74
	v_lshlrev_b64 v[34:35], 12, v[74:75]
	v_lshl_add_u64 v[32:33], v[32:33], 0, v[34:35]
	v_lshl_add_u64 v[32:33], v[32:33], 0, v[176:177]
	v_mul_f32_e32 v34, v40, v49
	global_atomic_add_f32 v[32:33], v34, off offset:128
	s_and_saveexec_b64 s[0:1], s[18:19]
	s_xor_b64 s[0:1], exec, s[0:1]
	s_mov_b64 s[2:3], s[92:93]
	s_or_saveexec_b64 s[0:1], s[0:1]
	s_waitcnt lgkmcnt(0)
	v_mov_b64_e32 v[32:33], s[2:3]
	s_xor_b64 exec, exec, s[0:1]
	v_mov_b64_e32 v[32:33], s[64:65]
	v_mov_b32_e32 v56, v92
	s_or_b64 exec, exec, s[0:1]
	v_ashrrev_i32_e32 v57, 31, v56
	v_lshlrev_b64 v[34:35], 12, v[56:57]
	v_lshl_add_u64 v[32:33], v[32:33], 0, v[34:35]
	v_lshl_add_u64 v[32:33], v[32:33], 0, v[176:177]
	v_mul_f32_e32 v34, v41, v49
	global_atomic_add_f32 v[32:33], v34, off offset:128
	s_and_saveexec_b64 s[0:1], s[20:21]
	s_xor_b64 s[0:1], exec, s[0:1]
	s_mov_b64 s[2:3], s[92:93]
	s_or_saveexec_b64 s[0:1], s[0:1]
	s_waitcnt lgkmcnt(0)
	v_mov_b64_e32 v[32:33], s[2:3]
	s_xor_b64 exec, exec, s[0:1]
	v_mov_b64_e32 v[32:33], s[64:65]
	v_mov_b32_e32 v76, v77
	s_or_b64 exec, exec, s[0:1]
	v_ashrrev_i32_e32 v77, 31, v76
	v_lshlrev_b64 v[34:35], 12, v[76:77]
	v_lshl_add_u64 v[32:33], v[32:33], 0, v[34:35]
	v_lshl_add_u64 v[32:33], v[32:33], 0, v[176:177]
	v_mul_f32_e32 v34, v42, v49
	global_atomic_add_f32 v[32:33], v34, off offset:128
	s_and_saveexec_b64 s[0:1], s[22:23]
	s_xor_b64 s[0:1], exec, s[0:1]
	s_mov_b64 s[2:3], s[92:93]
	s_or_saveexec_b64 s[0:1], s[0:1]
	s_waitcnt lgkmcnt(0)
	v_mov_b64_e32 v[32:33], s[2:3]
	s_xor_b64 exec, exec, s[0:1]
	v_mov_b64_e32 v[32:33], s[64:65]
	v_mov_b32_e32 v58, v93
	s_or_b64 exec, exec, s[0:1]
	v_ashrrev_i32_e32 v59, 31, v58
	v_lshlrev_b64 v[34:35], 12, v[58:59]
	v_lshl_add_u64 v[32:33], v[32:33], 0, v[34:35]
	v_lshl_add_u64 v[32:33], v[32:33], 0, v[176:177]
	v_mul_f32_e32 v34, v43, v49
	global_atomic_add_f32 v[32:33], v34, off offset:128
	s_and_saveexec_b64 s[0:1], s[24:25]
	s_xor_b64 s[0:1], exec, s[0:1]
	s_mov_b64 s[2:3], s[92:93]
	s_or_saveexec_b64 s[0:1], s[0:1]
	s_waitcnt lgkmcnt(0)
	v_mov_b64_e32 v[32:33], s[2:3]
	s_xor_b64 exec, exec, s[0:1]
	v_mov_b64_e32 v[32:33], s[64:65]
	v_mov_b32_e32 v78, v79
	s_or_b64 exec, exec, s[0:1]
	v_ashrrev_i32_e32 v79, 31, v78
	v_lshlrev_b64 v[34:35], 12, v[78:79]
	v_lshl_add_u64 v[32:33], v[32:33], 0, v[34:35]
	v_lshl_add_u64 v[32:33], v[32:33], 0, v[176:177]
	v_mul_f32_e32 v34, v44, v49
	global_atomic_add_f32 v[32:33], v34, off offset:128
	s_and_saveexec_b64 s[0:1], s[26:27]
	s_xor_b64 s[0:1], exec, s[0:1]
	s_mov_b64 s[2:3], s[92:93]
	s_or_saveexec_b64 s[0:1], s[0:1]
	s_waitcnt lgkmcnt(0)
	v_mov_b64_e32 v[32:33], s[2:3]
	s_xor_b64 exec, exec, s[0:1]
	v_mov_b64_e32 v[32:33], s[64:65]
	v_mov_b32_e32 v60, v94
	s_or_b64 exec, exec, s[0:1]
	v_ashrrev_i32_e32 v61, 31, v60
	v_lshlrev_b64 v[34:35], 12, v[60:61]
	v_lshl_add_u64 v[32:33], v[32:33], 0, v[34:35]
	v_lshl_add_u64 v[32:33], v[32:33], 0, v[176:177]
	v_mul_f32_e32 v34, v45, v49
	global_atomic_add_f32 v[32:33], v34, off offset:128
	s_and_saveexec_b64 s[0:1], s[28:29]
	s_xor_b64 s[0:1], exec, s[0:1]
	s_mov_b64 s[2:3], s[92:93]
	s_or_saveexec_b64 s[0:1], s[0:1]
	s_waitcnt lgkmcnt(0)
	v_mov_b64_e32 v[32:33], s[2:3]
	s_xor_b64 exec, exec, s[0:1]
	v_mov_b64_e32 v[32:33], s[64:65]
	v_mov_b32_e32 v80, v81
	s_or_b64 exec, exec, s[0:1]
	v_ashrrev_i32_e32 v81, 31, v80
	v_lshlrev_b64 v[34:35], 12, v[80:81]
	v_lshl_add_u64 v[32:33], v[32:33], 0, v[34:35]
	v_lshl_add_u64 v[32:33], v[32:33], 0, v[176:177]
	v_mul_f32_e32 v34, v46, v49
	global_atomic_add_f32 v[32:33], v34, off offset:128
	s_and_saveexec_b64 s[0:1], s[30:31]
	s_xor_b64 s[0:1], exec, s[0:1]
	s_mov_b64 s[2:3], s[92:93]
	s_or_saveexec_b64 s[0:1], s[0:1]
	s_waitcnt lgkmcnt(0)
	v_mov_b64_e32 v[32:33], s[2:3]
	s_xor_b64 exec, exec, s[0:1]
	v_mov_b64_e32 v[32:33], s[64:65]
	v_mov_b32_e32 v62, v95
	s_or_b64 exec, exec, s[0:1]
	v_ashrrev_i32_e32 v63, 31, v62
	v_lshlrev_b64 v[36:37], 12, v[62:63]
	v_lshl_add_u64 v[32:33], v[32:33], 0, v[36:37]
	v_lshl_add_u64 v[32:33], v[32:33], 0, v[176:177]
	v_mul_f32_e32 v36, v47, v49
	v_lshl_add_u64 v[34:35], s[62:63], 0, v[176:177]
	global_atomic_add_f32 v[32:33], v36, off offset:128
	global_load_dword v54, v[34:35], off
	v_add3_u32 v32, v86, v87, 32
	v_mul_hi_i32 v33, v32, s35
	v_lshrrev_b32_e32 v34, 31, v33
	v_ashrrev_i32_e32 v33, 11, v33
	v_add_u32_e32 v35, v33, v34
	v_mad_i32_i24 v38, v35, s33, v32
	v_lshlrev_b32_e32 v33, 13, v35
	v_cmp_lt_i32_e32 vcc, s82, v38
	v_add3_u32 v32, v33, v38, s79
	s_and_saveexec_b64 s[0:1], vcc
	s_xor_b64 s[0:1], exec, s[0:1]
	s_mov_b64 s[2:3], s[92:93]
	v_add3_u32 v34, v33, v38, s79
	s_or_saveexec_b64 s[0:1], s[0:1]
	s_waitcnt lgkmcnt(0)
	v_mov_b64_e32 v[36:37], s[2:3]
	v_lshl_add_u32 v33, v35, 8, v38
	s_xor_b64 exec, exec, s[0:1]
	v_lshl_add_u32 v34, v35, 8, v38
	v_mov_b64_e32 v[36:37], s[64:65]
	s_or_b64 exec, exec, s[0:1]
	v_ashrrev_i32_e32 v35, 31, v34
	v_lshlrev_b64 v[34:35], 12, v[34:35]
	v_lshl_add_u64 v[34:35], v[36:37], 0, v[34:35]
	v_lshl_add_u64 v[34:35], v[34:35], 0, v[176:177]
	s_waitcnt vmcnt(0)
	v_mul_f32_e32 v16, v16, v54
	global_atomic_add_f32 v[34:35], v16, off
	v_add3_u32 v16, v86, v87, 33
	v_mul_hi_i32 v34, v16, s35
	v_lshrrev_b32_e32 v35, 31, v34
	v_ashrrev_i32_e32 v34, 11, v34
	v_add_u32_e32 v35, v34, v35
	v_mad_i32_i24 v38, v35, s33, v16
	v_lshlrev_b32_e32 v36, 13, v35
	v_cmp_lt_i32_e64 s[2:3], s82, v38
	v_add3_u32 v16, v36, v38, s79
	s_and_saveexec_b64 s[0:1], s[2:3]
	s_xor_b64 s[0:1], exec, s[0:1]
	s_mov_b64 s[4:5], s[92:93]
	v_add3_u32 v34, v36, v38, s79
	s_or_saveexec_b64 s[0:1], s[0:1]
	s_waitcnt lgkmcnt(0)
	v_mov_b64_e32 v[36:37], s[4:5]
	v_lshl_add_u32 v55, v35, 8, v38
	s_xor_b64 exec, exec, s[0:1]
	v_lshl_add_u32 v34, v35, 8, v38
	v_mov_b64_e32 v[36:37], s[64:65]
	s_or_b64 exec, exec, s[0:1]
	v_ashrrev_i32_e32 v35, 31, v34
	v_lshlrev_b64 v[34:35], 12, v[34:35]
	v_lshl_add_u64 v[34:35], v[36:37], 0, v[34:35]
	v_lshl_add_u64 v[34:35], v[34:35], 0, v[176:177]
	v_mul_f32_e32 v17, v17, v54
	global_atomic_add_f32 v[34:35], v17, off
	v_add3_u32 v34, v86, v87, 34
	v_mul_hi_i32 v17, v34, s35
	v_lshrrev_b32_e32 v35, 31, v17
	v_ashrrev_i32_e32 v17, 11, v17
	v_add_u32_e32 v17, v17, v35
	v_mad_i32_i24 v37, v17, s33, v34
	v_lshlrev_b32_e32 v35, 13, v17
	v_cmp_lt_i32_e64 s[4:5], s82, v37
	v_add3_u32 v34, v35, v37, s79
	s_and_saveexec_b64 s[0:1], s[4:5]
	s_xor_b64 s[0:1], exec, s[0:1]
	s_mov_b64 s[6:7], s[92:93]
	v_add3_u32 v36, v35, v37, s79
	s_or_saveexec_b64 s[0:1], s[0:1]
	s_waitcnt lgkmcnt(0)
	v_mov_b64_e32 v[38:39], s[6:7]
	v_lshl_add_u32 v35, v17, 8, v37
	s_xor_b64 exec, exec, s[0:1]
	v_lshl_add_u32 v36, v17, 8, v37
	v_mov_b64_e32 v[38:39], s[64:65]
	s_or_b64 exec, exec, s[0:1]
	v_ashrrev_i32_e32 v37, 31, v36
	v_lshlrev_b64 v[36:37], 12, v[36:37]
	v_lshl_add_u64 v[36:37], v[38:39], 0, v[36:37]
	v_lshl_add_u64 v[36:37], v[36:37], 0, v[176:177]
	v_mul_f32_e32 v17, v18, v54
	global_atomic_add_f32 v[36:37], v17, off
	v_add3_u32 v18, v86, v87, 35
	v_mul_hi_i32 v17, v18, s35
	v_lshrrev_b32_e32 v36, 31, v17
	v_ashrrev_i32_e32 v17, 11, v17
	v_add_u32_e32 v17, v17, v36
	v_mad_i32_i24 v37, v17, s33, v18
	v_lshlrev_b32_e32 v38, 13, v17
	v_cmp_lt_i32_e64 s[6:7], s82, v37
	v_add3_u32 v18, v38, v37, s79
	s_and_saveexec_b64 s[0:1], s[6:7]
	s_xor_b64 s[0:1], exec, s[0:1]
	s_mov_b64 s[8:9], s[92:93]
	v_add3_u32 v36, v38, v37, s79
	s_or_saveexec_b64 s[0:1], s[0:1]
	s_waitcnt lgkmcnt(0)
	v_mov_b64_e32 v[38:39], s[8:9]
	v_lshl_add_u32 v56, v17, 8, v37
	s_xor_b64 exec, exec, s[0:1]
	v_lshl_add_u32 v36, v17, 8, v37
	v_mov_b64_e32 v[38:39], s[64:65]
	s_or_b64 exec, exec, s[0:1]
	v_ashrrev_i32_e32 v37, 31, v36
	v_lshlrev_b64 v[36:37], 12, v[36:37]
	v_lshl_add_u64 v[36:37], v[38:39], 0, v[36:37]
	v_lshl_add_u64 v[36:37], v[36:37], 0, v[176:177]
	v_mul_f32_e32 v17, v19, v54
	global_atomic_add_f32 v[36:37], v17, off
	v_add3_u32 v19, v86, v87, 40
	v_mul_hi_i32 v17, v19, s35
	v_lshrrev_b32_e32 v36, 31, v17
	v_ashrrev_i32_e32 v17, 11, v17
	v_add_u32_e32 v17, v17, v36
	v_mad_i32_i24 v19, v17, s33, v19
	v_lshlrev_b32_e32 v37, 13, v17
	v_cmp_lt_i32_e64 s[8:9], s82, v19
	v_add3_u32 v36, v37, v19, s79
	s_and_saveexec_b64 s[0:1], s[8:9]
	s_xor_b64 s[0:1], exec, s[0:1]
	s_mov_b64 s[10:11], s[92:93]
	v_add3_u32 v38, v37, v19, s79
	s_or_saveexec_b64 s[0:1], s[0:1]
	s_waitcnt lgkmcnt(0)
	v_mov_b64_e32 v[40:41], s[10:11]
	v_lshl_add_u32 v37, v17, 8, v19
	s_xor_b64 exec, exec, s[0:1]
	v_lshl_add_u32 v38, v17, 8, v19
	v_mov_b64_e32 v[40:41], s[64:65]
	s_or_b64 exec, exec, s[0:1]
	v_ashrrev_i32_e32 v39, 31, v38
	v_lshlrev_b64 v[38:39], 12, v[38:39]
	v_lshl_add_u64 v[38:39], v[40:41], 0, v[38:39]
	v_lshl_add_u64 v[38:39], v[38:39], 0, v[176:177]
	v_mul_f32_e32 v17, v20, v54
	global_atomic_add_f32 v[38:39], v17, off
	v_add3_u32 v19, v86, v87, 41
	v_mul_hi_i32 v17, v19, s35
	v_lshrrev_b32_e32 v20, 31, v17
	v_ashrrev_i32_e32 v17, 11, v17
	v_add_u32_e32 v17, v17, v20
	v_mad_i32_i24 v19, v17, s33, v19
	v_lshlrev_b32_e32 v39, 13, v17
	v_cmp_lt_i32_e64 s[10:11], s82, v19
	v_add3_u32 v20, v39, v19, s79
	s_and_saveexec_b64 s[0:1], s[10:11]
	s_xor_b64 s[0:1], exec, s[0:1]
	s_mov_b64 s[12:13], s[92:93]
	v_add3_u32 v38, v39, v19, s79
	s_or_saveexec_b64 s[0:1], s[0:1]
	s_waitcnt lgkmcnt(0)
	v_mov_b64_e32 v[40:41], s[12:13]
	v_lshl_add_u32 v57, v17, 8, v19
	s_xor_b64 exec, exec, s[0:1]
	v_lshl_add_u32 v38, v17, 8, v19
	v_mov_b64_e32 v[40:41], s[64:65]
	s_or_b64 exec, exec, s[0:1]
	v_ashrrev_i32_e32 v39, 31, v38
	v_lshlrev_b64 v[38:39], 12, v[38:39]
	v_lshl_add_u64 v[38:39], v[40:41], 0, v[38:39]
	v_lshl_add_u64 v[38:39], v[38:39], 0, v[176:177]
	v_mul_f32_e32 v17, v21, v54
	global_atomic_add_f32 v[38:39], v17, off
	v_add3_u32 v19, v86, v87, 42
	v_mul_hi_i32 v17, v19, s35
	v_lshrrev_b32_e32 v21, 31, v17
	v_ashrrev_i32_e32 v17, 11, v17
	v_add_u32_e32 v17, v17, v21
	v_mad_i32_i24 v19, v17, s33, v19
	v_lshlrev_b32_e32 v21, 13, v17
	v_cmp_lt_i32_e64 s[12:13], s82, v19
	v_add3_u32 v38, v21, v19, s79
	s_and_saveexec_b64 s[0:1], s[12:13]
	s_xor_b64 s[0:1], exec, s[0:1]
	s_mov_b64 s[14:15], s[92:93]
	v_add3_u32 v40, v21, v19, s79
	s_or_saveexec_b64 s[0:1], s[0:1]
	s_waitcnt lgkmcnt(0)
	v_mov_b64_e32 v[42:43], s[14:15]
	v_lshl_add_u32 v39, v17, 8, v19
	s_xor_b64 exec, exec, s[0:1]
	v_lshl_add_u32 v40, v17, 8, v19
	v_mov_b64_e32 v[42:43], s[64:65]
	s_or_b64 exec, exec, s[0:1]
	v_ashrrev_i32_e32 v41, 31, v40
	v_lshlrev_b64 v[40:41], 12, v[40:41]
	v_lshl_add_u64 v[40:41], v[42:43], 0, v[40:41]
	v_lshl_add_u64 v[40:41], v[40:41], 0, v[176:177]
	v_mul_f32_e32 v17, v22, v54
	global_atomic_add_f32 v[40:41], v17, off
	v_add3_u32 v19, v86, v87, 43
	v_mul_hi_i32 v17, v19, s35
	v_lshrrev_b32_e32 v21, 31, v17
	v_ashrrev_i32_e32 v17, 11, v17
	v_add_u32_e32 v17, v17, v21
	v_mad_i32_i24 v19, v17, s33, v19
	v_lshlrev_b32_e32 v21, 13, v17
	v_cmp_lt_i32_e64 s[14:15], s82, v19
	v_add3_u32 v22, v21, v19, s79
	s_and_saveexec_b64 s[0:1], s[14:15]
	s_xor_b64 s[0:1], exec, s[0:1]
	s_mov_b64 s[16:17], s[92:93]
	v_add3_u32 v40, v21, v19, s79
	s_or_saveexec_b64 s[0:1], s[0:1]
	s_waitcnt lgkmcnt(0)
	v_mov_b64_e32 v[42:43], s[16:17]
	v_lshl_add_u32 v58, v17, 8, v19
	s_xor_b64 exec, exec, s[0:1]
	v_lshl_add_u32 v40, v17, 8, v19
	v_mov_b64_e32 v[42:43], s[64:65]
	s_or_b64 exec, exec, s[0:1]
	v_ashrrev_i32_e32 v41, 31, v40
	v_lshlrev_b64 v[40:41], 12, v[40:41]
	v_lshl_add_u64 v[40:41], v[42:43], 0, v[40:41]
	v_lshl_add_u64 v[40:41], v[40:41], 0, v[176:177]
	v_mul_f32_e32 v17, v23, v54
	global_atomic_add_f32 v[40:41], v17, off
	v_add3_u32 v19, v86, v87, 48
	v_mul_hi_i32 v17, v19, s35
	v_lshrrev_b32_e32 v21, 31, v17
	v_ashrrev_i32_e32 v17, 11, v17
	v_add_u32_e32 v17, v17, v21
	v_mad_i32_i24 v19, v17, s33, v19
	v_lshlrev_b32_e32 v21, 13, v17
	v_cmp_lt_i32_e64 s[16:17], s82, v19
	v_add3_u32 v40, v21, v19, s79
	s_and_saveexec_b64 s[0:1], s[16:17]
	s_xor_b64 s[0:1], exec, s[0:1]
	s_mov_b64 s[18:19], s[92:93]
	v_add3_u32 v42, v21, v19, s79
	s_or_saveexec_b64 s[0:1], s[0:1]
	s_waitcnt lgkmcnt(0)
	v_mov_b64_e32 v[44:45], s[18:19]
	v_lshl_add_u32 v41, v17, 8, v19
	s_xor_b64 exec, exec, s[0:1]
	v_lshl_add_u32 v42, v17, 8, v19
	v_mov_b64_e32 v[44:45], s[64:65]
	s_or_b64 exec, exec, s[0:1]
	v_ashrrev_i32_e32 v43, 31, v42
	v_lshlrev_b64 v[42:43], 12, v[42:43]
	v_lshl_add_u64 v[42:43], v[44:45], 0, v[42:43]
	v_lshl_add_u64 v[42:43], v[42:43], 0, v[176:177]
	v_mul_f32_e32 v17, v24, v54
	global_atomic_add_f32 v[42:43], v17, off
	v_add3_u32 v19, v86, v87, 49
	v_mul_hi_i32 v17, v19, s35
	v_lshrrev_b32_e32 v21, 31, v17
	v_ashrrev_i32_e32 v17, 11, v17
	v_add_u32_e32 v17, v17, v21
	v_mad_i32_i24 v19, v17, s33, v19
	v_lshlrev_b32_e32 v21, 13, v17
	v_cmp_lt_i32_e64 s[18:19], s82, v19
	v_add3_u32 v24, v21, v19, s79
	s_and_saveexec_b64 s[0:1], s[18:19]
	s_xor_b64 s[0:1], exec, s[0:1]
	s_mov_b64 s[20:21], s[92:93]
	v_add3_u32 v42, v21, v19, s79
	s_or_saveexec_b64 s[0:1], s[0:1]
	s_waitcnt lgkmcnt(0)
	v_mov_b64_e32 v[44:45], s[20:21]
	v_lshl_add_u32 v59, v17, 8, v19
	s_xor_b64 exec, exec, s[0:1]
	v_lshl_add_u32 v42, v17, 8, v19
	v_mov_b64_e32 v[44:45], s[64:65]
	s_or_b64 exec, exec, s[0:1]
	v_ashrrev_i32_e32 v43, 31, v42
	v_lshlrev_b64 v[42:43], 12, v[42:43]
	v_lshl_add_u64 v[42:43], v[44:45], 0, v[42:43]
	v_lshl_add_u64 v[42:43], v[42:43], 0, v[176:177]
	v_mul_f32_e32 v17, v25, v54
	global_atomic_add_f32 v[42:43], v17, off
	v_add3_u32 v19, v86, v87, 50
	v_mul_hi_i32 v17, v19, s35
	v_lshrrev_b32_e32 v21, 31, v17
	v_ashrrev_i32_e32 v17, 11, v17
	v_add_u32_e32 v17, v17, v21
	v_mad_i32_i24 v19, v17, s33, v19
	v_lshlrev_b32_e32 v21, 13, v17
	v_cmp_lt_i32_e64 s[20:21], s82, v19
	v_add3_u32 v42, v21, v19, s79
	s_and_saveexec_b64 s[0:1], s[20:21]
	s_xor_b64 s[0:1], exec, s[0:1]
	s_mov_b64 s[22:23], s[92:93]
	v_add3_u32 v44, v21, v19, s79
	s_or_saveexec_b64 s[0:1], s[0:1]
	s_waitcnt lgkmcnt(0)
	v_mov_b64_e32 v[46:47], s[22:23]
	v_lshl_add_u32 v43, v17, 8, v19
	s_xor_b64 exec, exec, s[0:1]
	v_lshl_add_u32 v44, v17, 8, v19
	v_mov_b64_e32 v[46:47], s[64:65]
	s_or_b64 exec, exec, s[0:1]
	v_ashrrev_i32_e32 v45, 31, v44
	v_lshlrev_b64 v[44:45], 12, v[44:45]
	v_lshl_add_u64 v[44:45], v[46:47], 0, v[44:45]
	v_lshl_add_u64 v[44:45], v[44:45], 0, v[176:177]
	v_mul_f32_e32 v17, v26, v54
	global_atomic_add_f32 v[44:45], v17, off
	v_add3_u32 v19, v86, v87, 51
	v_mul_hi_i32 v17, v19, s35
	v_lshrrev_b32_e32 v21, 31, v17
	v_ashrrev_i32_e32 v17, 11, v17
	v_add_u32_e32 v17, v17, v21
	v_mad_i32_i24 v19, v17, s33, v19
	v_lshlrev_b32_e32 v21, 13, v17
	v_cmp_lt_i32_e64 s[22:23], s82, v19
	v_add3_u32 v26, v21, v19, s79
	s_and_saveexec_b64 s[0:1], s[22:23]
	s_xor_b64 s[0:1], exec, s[0:1]
	s_mov_b64 s[24:25], s[92:93]
	v_add3_u32 v44, v21, v19, s79
	s_or_saveexec_b64 s[0:1], s[0:1]
	s_waitcnt lgkmcnt(0)
	v_mov_b64_e32 v[46:47], s[24:25]
	v_lshl_add_u32 v60, v17, 8, v19
	s_xor_b64 exec, exec, s[0:1]
	v_lshl_add_u32 v44, v17, 8, v19
	v_mov_b64_e32 v[46:47], s[64:65]
	s_or_b64 exec, exec, s[0:1]
	v_ashrrev_i32_e32 v45, 31, v44
	v_lshlrev_b64 v[44:45], 12, v[44:45]
	v_lshl_add_u64 v[44:45], v[46:47], 0, v[44:45]
	v_lshl_add_u64 v[44:45], v[44:45], 0, v[176:177]
	v_mul_f32_e32 v17, v27, v54
	global_atomic_add_f32 v[44:45], v17, off
	v_add3_u32 v19, v86, v87, 56
	v_mul_hi_i32 v17, v19, s35
	v_lshrrev_b32_e32 v21, 31, v17
	v_ashrrev_i32_e32 v17, 11, v17
	v_add_u32_e32 v17, v17, v21
	v_mad_i32_i24 v19, v17, s33, v19
	v_lshlrev_b32_e32 v21, 13, v17
	v_cmp_lt_i32_e64 s[24:25], s82, v19
	v_add3_u32 v44, v21, v19, s79
	s_and_saveexec_b64 s[0:1], s[24:25]
	s_xor_b64 s[0:1], exec, s[0:1]
	s_mov_b64 s[26:27], s[92:93]
	v_add3_u32 v46, v21, v19, s79
	s_or_saveexec_b64 s[0:1], s[0:1]
	s_waitcnt lgkmcnt(0)
	v_mov_b64_e32 v[50:51], s[26:27]
	v_lshl_add_u32 v45, v17, 8, v19
	s_xor_b64 exec, exec, s[0:1]
	v_lshl_add_u32 v46, v17, 8, v19
	v_mov_b64_e32 v[50:51], s[64:65]
	s_or_b64 exec, exec, s[0:1]
	v_ashrrev_i32_e32 v47, 31, v46
	v_lshlrev_b64 v[46:47], 12, v[46:47]
	v_lshl_add_u64 v[46:47], v[50:51], 0, v[46:47]
	v_lshl_add_u64 v[46:47], v[46:47], 0, v[176:177]
	v_mul_f32_e32 v17, v28, v54
	global_atomic_add_f32 v[46:47], v17, off
	v_add3_u32 v19, v86, v87, 57
	v_mul_hi_i32 v17, v19, s35
	v_lshrrev_b32_e32 v21, 31, v17
	v_ashrrev_i32_e32 v17, 11, v17
	v_add_u32_e32 v17, v17, v21
	v_mad_i32_i24 v19, v17, s33, v19
	v_lshlrev_b32_e32 v21, 13, v17
	v_cmp_lt_i32_e64 s[26:27], s82, v19
	v_add3_u32 v28, v21, v19, s79
	s_and_saveexec_b64 s[0:1], s[26:27]
	s_xor_b64 s[0:1], exec, s[0:1]
	s_mov_b64 s[28:29], s[92:93]
	v_add3_u32 v46, v21, v19, s79
	s_or_saveexec_b64 s[0:1], s[0:1]
	s_waitcnt lgkmcnt(0)
	v_mov_b64_e32 v[50:51], s[28:29]
	v_lshl_add_u32 v61, v17, 8, v19
	s_xor_b64 exec, exec, s[0:1]
	v_lshl_add_u32 v46, v17, 8, v19
	v_mov_b64_e32 v[50:51], s[64:65]
	s_or_b64 exec, exec, s[0:1]
	v_ashrrev_i32_e32 v47, 31, v46
	v_lshlrev_b64 v[46:47], 12, v[46:47]
	v_lshl_add_u64 v[46:47], v[50:51], 0, v[46:47]
	v_lshl_add_u64 v[46:47], v[46:47], 0, v[176:177]
	v_mul_f32_e32 v17, v29, v54
	global_atomic_add_f32 v[46:47], v17, off
	v_add3_u32 v19, v86, v87, 58
	v_mul_hi_i32 v17, v19, s35
	v_lshrrev_b32_e32 v21, 31, v17
	v_ashrrev_i32_e32 v17, 11, v17
	v_add_u32_e32 v17, v17, v21
	v_mad_i32_i24 v19, v17, s33, v19
	v_lshlrev_b32_e32 v21, 13, v17
	v_cmp_lt_i32_e64 s[28:29], s82, v19
	v_add3_u32 v46, v21, v19, s79
	s_and_saveexec_b64 s[0:1], s[28:29]
	s_xor_b64 s[0:1], exec, s[0:1]
	s_mov_b64 s[30:31], s[92:93]
	v_add3_u32 v50, v21, v19, s79
	s_or_saveexec_b64 s[0:1], s[0:1]
	s_waitcnt lgkmcnt(0)
	v_mov_b64_e32 v[52:53], s[30:31]
	v_lshl_add_u32 v47, v17, 8, v19
	s_xor_b64 exec, exec, s[0:1]
	v_lshl_add_u32 v50, v17, 8, v19
	v_mov_b64_e32 v[52:53], s[64:65]
	s_or_b64 exec, exec, s[0:1]
	v_ashrrev_i32_e32 v51, 31, v50
	v_lshlrev_b64 v[50:51], 12, v[50:51]
	v_lshl_add_u64 v[50:51], v[52:53], 0, v[50:51]
	v_lshl_add_u64 v[50:51], v[50:51], 0, v[176:177]
	v_mul_f32_e32 v17, v30, v54
	global_atomic_add_f32 v[50:51], v17, off
	v_add3_u32 v19, v86, v87, 59
	v_mul_hi_i32 v17, v19, s35
	v_lshrrev_b32_e32 v21, 31, v17
	v_ashrrev_i32_e32 v17, 11, v17
	v_add_u32_e32 v17, v17, v21
	v_mad_i32_i24 v19, v17, s33, v19
	v_lshlrev_b32_e32 v21, 13, v17
	v_cmp_lt_i32_e64 s[30:31], s82, v19
	v_add3_u32 v30, v21, v19, s79
	s_and_saveexec_b64 s[0:1], s[30:31]
	s_xor_b64 s[0:1], exec, s[0:1]
	s_mov_b64 s[74:75], s[92:93]
	v_add3_u32 v50, v21, v19, s79
	s_or_saveexec_b64 s[0:1], s[0:1]
	s_waitcnt lgkmcnt(0)
	v_mov_b64_e32 v[52:53], s[74:75]
	v_lshl_add_u32 v62, v17, 8, v19
	s_xor_b64 exec, exec, s[0:1]
	v_lshl_add_u32 v50, v17, 8, v19
	v_mov_b64_e32 v[52:53], s[64:65]
	s_or_b64 exec, exec, s[0:1]
	v_ashrrev_i32_e32 v51, 31, v50
	v_lshlrev_b64 v[50:51], 12, v[50:51]
	v_lshl_add_u64 v[50:51], v[52:53], 0, v[50:51]
	v_mov_b32_e32 v49, v177
	v_lshl_add_u64 v[50:51], v[50:51], 0, v[176:177]
	v_mul_f32_e32 v17, v31, v54
	v_lshl_add_u64 v[48:49], s[62:63], 0, v[48:49]
	global_atomic_add_f32 v[50:51], v17, off
	global_load_dword v50, v[48:49], off
	s_and_saveexec_b64 s[0:1], vcc
	s_xor_b64 s[0:1], exec, s[0:1]
	s_mov_b64 s[74:75], s[92:93]
	s_or_saveexec_b64 s[0:1], s[0:1]
	s_waitcnt lgkmcnt(0)
	v_mov_b64_e32 v[48:49], s[74:75]
	s_xor_b64 exec, exec, s[0:1]
	v_mov_b64_e32 v[48:49], s[64:65]
	v_mov_b32_e32 v32, v33
	s_or_b64 exec, exec, s[0:1]
	v_ashrrev_i32_e32 v33, 31, v32
	v_lshlrev_b64 v[32:33], 12, v[32:33]
	v_lshl_add_u64 v[32:33], v[48:49], 0, v[32:33]
	v_lshl_add_u64 v[32:33], v[32:33], 0, v[176:177]
	s_waitcnt vmcnt(0)
	v_mul_f32_e32 v0, v0, v50
	global_atomic_add_f32 v[32:33], v0, off offset:128
	s_and_saveexec_b64 s[0:1], s[2:3]
	s_xor_b64 s[0:1], exec, s[0:1]
	s_mov_b64 s[74:75], s[92:93]
	s_or_saveexec_b64 s[0:1], s[0:1]
	s_waitcnt lgkmcnt(0)
	v_mov_b64_e32 v[32:33], s[74:75]
	s_xor_b64 exec, exec, s[0:1]
	v_mov_b64_e32 v[32:33], s[64:65]
	v_mov_b32_e32 v16, v55
	s_or_b64 exec, exec, s[0:1]
	v_ashrrev_i32_e32 v17, 31, v16
	v_lshlrev_b64 v[16:17], 12, v[16:17]
	v_lshl_add_u64 v[16:17], v[32:33], 0, v[16:17]
	v_lshl_add_u64 v[16:17], v[16:17], 0, v[176:177]
	v_mul_f32_e32 v0, v1, v50
	global_atomic_add_f32 v[16:17], v0, off offset:128
	s_and_saveexec_b64 s[0:1], s[4:5]
	s_xor_b64 s[0:1], exec, s[0:1]
	s_mov_b64 s[2:3], s[92:93]
	s_or_saveexec_b64 s[0:1], s[0:1]
	s_waitcnt lgkmcnt(0)
	v_mov_b64_e32 v[0:1], s[2:3]
	s_xor_b64 exec, exec, s[0:1]
	v_mov_b64_e32 v[0:1], s[64:65]
	v_mov_b32_e32 v34, v35
	s_or_b64 exec, exec, s[0:1]
	v_ashrrev_i32_e32 v35, 31, v34
	v_lshlrev_b64 v[16:17], 12, v[34:35]
	v_lshl_add_u64 v[0:1], v[0:1], 0, v[16:17]
	v_lshl_add_u64 v[0:1], v[0:1], 0, v[176:177]
	v_mul_f32_e32 v2, v2, v50
	global_atomic_add_f32 v[0:1], v2, off offset:128
	s_and_saveexec_b64 s[0:1], s[6:7]
	s_xor_b64 s[0:1], exec, s[0:1]
	s_mov_b64 s[2:3], s[92:93]
	s_or_saveexec_b64 s[0:1], s[0:1]
	s_waitcnt lgkmcnt(0)
	v_mov_b64_e32 v[0:1], s[2:3]
	s_xor_b64 exec, exec, s[0:1]
	v_mov_b64_e32 v[0:1], s[64:65]
	v_mov_b32_e32 v18, v56
	s_or_b64 exec, exec, s[0:1]
	v_ashrrev_i32_e32 v19, 31, v18
	v_lshlrev_b64 v[16:17], 12, v[18:19]
	v_lshl_add_u64 v[0:1], v[0:1], 0, v[16:17]
	v_lshl_add_u64 v[0:1], v[0:1], 0, v[176:177]
	v_mul_f32_e32 v2, v3, v50
	global_atomic_add_f32 v[0:1], v2, off offset:128
	s_and_saveexec_b64 s[0:1], s[8:9]
	s_xor_b64 s[0:1], exec, s[0:1]
	s_mov_b64 s[2:3], s[92:93]
	s_or_saveexec_b64 s[0:1], s[0:1]
	s_waitcnt lgkmcnt(0)
	v_mov_b64_e32 v[0:1], s[2:3]
	s_xor_b64 exec, exec, s[0:1]
	v_mov_b64_e32 v[0:1], s[64:65]
	v_mov_b32_e32 v36, v37
	s_or_b64 exec, exec, s[0:1]
	v_ashrrev_i32_e32 v37, 31, v36
	v_lshlrev_b64 v[2:3], 12, v[36:37]
	v_lshl_add_u64 v[0:1], v[0:1], 0, v[2:3]
	v_lshl_add_u64 v[0:1], v[0:1], 0, v[176:177]
	v_mul_f32_e32 v2, v4, v50
	global_atomic_add_f32 v[0:1], v2, off offset:128
	s_and_saveexec_b64 s[0:1], s[10:11]
	s_xor_b64 s[0:1], exec, s[0:1]
	s_mov_b64 s[2:3], s[92:93]
	s_or_saveexec_b64 s[0:1], s[0:1]
	s_waitcnt lgkmcnt(0)
	v_mov_b64_e32 v[0:1], s[2:3]
	s_xor_b64 exec, exec, s[0:1]
	v_mov_b64_e32 v[0:1], s[64:65]
	v_mov_b32_e32 v20, v57
	s_or_b64 exec, exec, s[0:1]
	v_ashrrev_i32_e32 v21, 31, v20
	v_lshlrev_b64 v[2:3], 12, v[20:21]
	v_lshl_add_u64 v[0:1], v[0:1], 0, v[2:3]
	v_lshl_add_u64 v[0:1], v[0:1], 0, v[176:177]
	v_mul_f32_e32 v2, v5, v50
	global_atomic_add_f32 v[0:1], v2, off offset:128
	s_and_saveexec_b64 s[0:1], s[12:13]
	s_xor_b64 s[0:1], exec, s[0:1]
	s_mov_b64 s[2:3], s[92:93]
	s_or_saveexec_b64 s[0:1], s[0:1]
	s_waitcnt lgkmcnt(0)
	v_mov_b64_e32 v[0:1], s[2:3]
	s_xor_b64 exec, exec, s[0:1]
	v_mov_b64_e32 v[0:1], s[64:65]
	v_mov_b32_e32 v38, v39
	s_or_b64 exec, exec, s[0:1]
	v_ashrrev_i32_e32 v39, 31, v38
	v_lshlrev_b64 v[2:3], 12, v[38:39]
	v_lshl_add_u64 v[0:1], v[0:1], 0, v[2:3]
	v_lshl_add_u64 v[0:1], v[0:1], 0, v[176:177]
	v_mul_f32_e32 v2, v6, v50
	global_atomic_add_f32 v[0:1], v2, off offset:128
	s_and_saveexec_b64 s[0:1], s[14:15]
	s_xor_b64 s[0:1], exec, s[0:1]
	s_mov_b64 s[2:3], s[92:93]
	s_or_saveexec_b64 s[0:1], s[0:1]
	s_waitcnt lgkmcnt(0)
	v_mov_b64_e32 v[0:1], s[2:3]
	s_xor_b64 exec, exec, s[0:1]
	v_mov_b64_e32 v[0:1], s[64:65]
	v_mov_b32_e32 v22, v58
	s_or_b64 exec, exec, s[0:1]
	v_ashrrev_i32_e32 v23, 31, v22
	v_lshlrev_b64 v[2:3], 12, v[22:23]
	v_lshl_add_u64 v[0:1], v[0:1], 0, v[2:3]
	v_lshl_add_u64 v[0:1], v[0:1], 0, v[176:177]
	v_mul_f32_e32 v2, v7, v50
	global_atomic_add_f32 v[0:1], v2, off offset:128
	s_and_saveexec_b64 s[0:1], s[16:17]
	s_xor_b64 s[0:1], exec, s[0:1]
	s_mov_b64 s[2:3], s[92:93]
	s_or_saveexec_b64 s[0:1], s[0:1]
	s_waitcnt lgkmcnt(0)
	v_mov_b64_e32 v[0:1], s[2:3]
	s_xor_b64 exec, exec, s[0:1]
	v_mov_b64_e32 v[0:1], s[64:65]
	v_mov_b32_e32 v40, v41
	s_or_b64 exec, exec, s[0:1]
	v_ashrrev_i32_e32 v41, 31, v40
	v_lshlrev_b64 v[2:3], 12, v[40:41]
	v_lshl_add_u64 v[0:1], v[0:1], 0, v[2:3]
	v_lshl_add_u64 v[0:1], v[0:1], 0, v[176:177]
	v_mul_f32_e32 v2, v8, v50
	global_atomic_add_f32 v[0:1], v2, off offset:128
	s_and_saveexec_b64 s[0:1], s[18:19]
	s_xor_b64 s[0:1], exec, s[0:1]
	s_mov_b64 s[2:3], s[92:93]
	s_or_saveexec_b64 s[0:1], s[0:1]
	s_waitcnt lgkmcnt(0)
	v_mov_b64_e32 v[0:1], s[2:3]
	s_xor_b64 exec, exec, s[0:1]
	v_mov_b64_e32 v[0:1], s[64:65]
	v_mov_b32_e32 v24, v59
	s_or_b64 exec, exec, s[0:1]
	v_ashrrev_i32_e32 v25, 31, v24
	v_lshlrev_b64 v[2:3], 12, v[24:25]
	v_lshl_add_u64 v[0:1], v[0:1], 0, v[2:3]
	v_lshl_add_u64 v[0:1], v[0:1], 0, v[176:177]
	v_mul_f32_e32 v2, v9, v50
	global_atomic_add_f32 v[0:1], v2, off offset:128
	s_and_saveexec_b64 s[0:1], s[20:21]
	s_xor_b64 s[0:1], exec, s[0:1]
	s_mov_b64 s[2:3], s[92:93]
	s_or_saveexec_b64 s[0:1], s[0:1]
	s_waitcnt lgkmcnt(0)
	v_mov_b64_e32 v[0:1], s[2:3]
	s_xor_b64 exec, exec, s[0:1]
	v_mov_b64_e32 v[0:1], s[64:65]
	v_mov_b32_e32 v42, v43
	s_or_b64 exec, exec, s[0:1]
	v_ashrrev_i32_e32 v43, 31, v42
	v_lshlrev_b64 v[2:3], 12, v[42:43]
	v_lshl_add_u64 v[0:1], v[0:1], 0, v[2:3]
	v_lshl_add_u64 v[0:1], v[0:1], 0, v[176:177]
	v_mul_f32_e32 v2, v10, v50
	global_atomic_add_f32 v[0:1], v2, off offset:128
	s_and_saveexec_b64 s[0:1], s[22:23]
	s_xor_b64 s[0:1], exec, s[0:1]
	s_mov_b64 s[2:3], s[92:93]
	s_or_saveexec_b64 s[0:1], s[0:1]
	s_waitcnt lgkmcnt(0)
	v_mov_b64_e32 v[0:1], s[2:3]
	s_xor_b64 exec, exec, s[0:1]
	v_mov_b64_e32 v[0:1], s[64:65]
	v_mov_b32_e32 v26, v60
	s_or_b64 exec, exec, s[0:1]
	v_ashrrev_i32_e32 v27, 31, v26
	v_lshlrev_b64 v[2:3], 12, v[26:27]
	v_lshl_add_u64 v[0:1], v[0:1], 0, v[2:3]
	v_lshl_add_u64 v[0:1], v[0:1], 0, v[176:177]
	v_mul_f32_e32 v2, v11, v50
	global_atomic_add_f32 v[0:1], v2, off offset:128
	s_and_saveexec_b64 s[0:1], s[24:25]
	s_xor_b64 s[0:1], exec, s[0:1]
	s_mov_b64 s[2:3], s[92:93]
	s_or_saveexec_b64 s[0:1], s[0:1]
	s_waitcnt lgkmcnt(0)
	v_mov_b64_e32 v[0:1], s[2:3]
	s_xor_b64 exec, exec, s[0:1]
	v_mov_b64_e32 v[0:1], s[64:65]
	v_mov_b32_e32 v44, v45
	s_or_b64 exec, exec, s[0:1]
	v_ashrrev_i32_e32 v45, 31, v44
	v_lshlrev_b64 v[2:3], 12, v[44:45]
	v_lshl_add_u64 v[0:1], v[0:1], 0, v[2:3]
	v_lshl_add_u64 v[0:1], v[0:1], 0, v[176:177]
	v_mul_f32_e32 v2, v12, v50
	global_atomic_add_f32 v[0:1], v2, off offset:128
	s_and_saveexec_b64 s[0:1], s[26:27]
	s_xor_b64 s[0:1], exec, s[0:1]
	s_mov_b64 s[2:3], s[92:93]
	s_or_saveexec_b64 s[0:1], s[0:1]
	s_waitcnt lgkmcnt(0)
	v_mov_b64_e32 v[0:1], s[2:3]
	s_xor_b64 exec, exec, s[0:1]
	v_mov_b64_e32 v[0:1], s[64:65]
	v_mov_b32_e32 v28, v61
	s_or_b64 exec, exec, s[0:1]
	v_ashrrev_i32_e32 v29, 31, v28
	v_lshlrev_b64 v[2:3], 12, v[28:29]
	v_lshl_add_u64 v[0:1], v[0:1], 0, v[2:3]
	v_lshl_add_u64 v[0:1], v[0:1], 0, v[176:177]
	v_mul_f32_e32 v2, v13, v50
	global_atomic_add_f32 v[0:1], v2, off offset:128
	s_and_saveexec_b64 s[0:1], s[28:29]
	s_xor_b64 s[0:1], exec, s[0:1]
	s_mov_b64 s[2:3], s[92:93]
	s_or_saveexec_b64 s[0:1], s[0:1]
	s_waitcnt lgkmcnt(0)
	v_mov_b64_e32 v[0:1], s[2:3]
	s_xor_b64 exec, exec, s[0:1]
	v_mov_b64_e32 v[0:1], s[64:65]
	v_mov_b32_e32 v46, v47
	s_or_b64 exec, exec, s[0:1]
	v_ashrrev_i32_e32 v47, 31, v46
	v_lshlrev_b64 v[2:3], 12, v[46:47]
	v_lshl_add_u64 v[0:1], v[0:1], 0, v[2:3]
	v_lshl_add_u64 v[0:1], v[0:1], 0, v[176:177]
	v_mul_f32_e32 v2, v14, v50
	global_atomic_add_f32 v[0:1], v2, off offset:128
	s_and_saveexec_b64 s[0:1], s[30:31]
	s_xor_b64 s[0:1], exec, s[0:1]
	s_mov_b64 s[2:3], s[92:93]
	s_or_saveexec_b64 s[0:1], s[0:1]
	s_waitcnt lgkmcnt(0)
	v_mov_b64_e32 v[0:1], s[2:3]
	s_xor_b64 exec, exec, s[0:1]
	s_cbranch_execz .LBB0_687
	v_mov_b64_e32 v[0:1], s[64:65]
	v_mov_b32_e32 v30, v62
	s_branch .LBB0_687

.LBB0_1173:
	s_mul_i32 s8, s5, 0xc000
	v_add_u32_e32 v87, s8, v83
	v_add_u32_e32 v90, 0x2000, v87
	v_readfirstlane_b32 s8, v87
	v_lshl_add_u64 v[88:89], v[74:75], 0, s[2:3]
	s_mov_b32 m0, s8
	v_readfirstlane_b32 s8, v90
	v_add_u32_e32 v90, 0x4000, v87
	s_waitcnt vmcnt(6)
	s_barrier
	global_load_lds_dwordx4 v[88:89], off
	v_lshl_add_u64 v[88:89], v[72:73], 0, s[2:3]
	s_mov_b32 m0, s8
	v_readfirstlane_b32 s8, v90
	v_add_u32_e32 v90, 0x6000, v87
	global_load_lds_dwordx4 v[88:89], off
	v_lshl_add_u64 v[88:89], v[70:71], 0, s[2:3]
	s_mov_b32 m0, s8
	v_readfirstlane_b32 s8, v90
	v_add_u32_e32 v90, 0x8000, v87
	global_load_lds_dwordx4 v[88:89], off
	v_lshl_add_u64 v[88:89], v[68:69], 0, s[2:3]
	s_mov_b32 m0, s8
	v_readfirstlane_b32 s8, v90
	v_add_u32_e32 v87, 0xa000, v87
	global_load_lds_dwordx4 v[88:89], off
	v_lshl_add_u64 v[88:89], v[66:67], 0, s[2:3]
	s_mov_b32 m0, s8
	v_readfirstlane_b32 s8, v87
	global_load_lds_dwordx4 v[88:89], off
	v_lshl_add_u64 v[88:89], v[64:65], 0, s[2:3]
	s_mov_b32 m0, s8
	s_mul_i32 s8, s7, 0xc000
	global_load_lds_dwordx4 v[88:89], off
	s_add_i32 s8, s8, 0
	v_add_u32_e32 v87, s8, v82
	v_add_u32_e32 v120, s8, v81
	v_add_u32_e32 v92, v87, v80
	v_add_u32_e32 v100, v120, v80
	v_add_u32_e32 v108, v87, v79
	v_add_u32_e32 v116, v120, v79
	ds_read_b128 v[88:91], v92
	ds_read_b128 v[92:95], v92 offset:4096
	ds_read_b128 v[96:99], v100 offset:32768
	ds_read_b128 v[100:103], v100 offset:36864
	ds_read_b128 v[104:107], v108
	ds_read_b128 v[108:111], v108 offset:4096
	ds_read_b128 v[112:115], v116 offset:32768
	ds_read_b128 v[116:119], v116 offset:36864
	s_waitcnt lgkmcnt(0)
	v_mfma_f32_32x32x16_bf16 v[48:63], v[88:91], v[96:99], v[48:63]
	v_mfma_f32_32x32x16_bf16 v[32:47], v[88:91], v[100:103], v[32:47]
	v_mfma_f32_32x32x16_bf16 v[16:31], v[92:95], v[96:99], v[16:31]
	v_add_u32_e32 v96, v87, v78
	ds_read_b128 v[88:91], v96
	v_mfma_f32_32x32x16_bf16 v[0:15], v[92:95], v[100:103], v[0:15]
	v_add_u32_e32 v100, v120, v78
	ds_read_b128 v[92:95], v100 offset:32768
	ds_read_b128 v[96:99], v96 offset:4096
	ds_read_b128 v[100:103], v100 offset:36864
	v_mfma_f32_32x32x16_bf16 v[48:63], v[104:107], v[112:115], v[48:63]
	v_add_u32_e32 v87, v87, v77
	v_mfma_f32_32x32x16_bf16 v[32:47], v[104:107], v[116:119], v[32:47]
	ds_read_b128 v[104:107], v87
	v_mfma_f32_32x32x16_bf16 v[16:31], v[108:111], v[112:115], v[16:31]
	v_mfma_f32_32x32x16_bf16 v[0:15], v[108:111], v[116:119], v[0:15]
	v_add_u32_e32 v116, v120, v77
	ds_read_b128 v[108:111], v116 offset:32768
	ds_read_b128 v[112:115], v87 offset:4096
	ds_read_b128 v[116:119], v116 offset:36864
	s_waitcnt lgkmcnt(0)
	v_mfma_f32_32x32x16_bf16 v[48:63], v[88:91], v[92:95], v[48:63]
	s_add_i32 s8, s7, 1
	s_cmp_lg_u32 s7, 2
	s_cselect_b32 s7, s8, 0
	s_add_i32 s8, s5, 1
	s_cmp_lg_u32 s5, 2
	s_cselect_b32 s5, s8, 0
	s_add_u32 s2, s2, 0x80
	v_mfma_f32_32x32x16_bf16 v[32:47], v[88:91], v[100:103], v[32:47]
	s_addc_u32 s3, s3, 0
	s_cmpk_eq_i32 s2, 0x480
	v_mfma_f32_32x32x16_bf16 v[16:31], v[96:99], v[92:95], v[16:31]
	v_mfma_f32_32x32x16_bf16 v[0:15], v[96:99], v[100:103], v[0:15]
	v_mfma_f32_32x32x16_bf16 v[48:63], v[104:107], v[108:111], v[48:63]
	v_mfma_f32_32x32x16_bf16 v[32:47], v[104:107], v[116:119], v[32:47]
	v_mfma_f32_32x32x16_bf16 v[16:31], v[112:115], v[108:111], v[16:31]
	v_mfma_f32_32x32x16_bf16 v[0:15], v[112:115], v[116:119], v[0:15]
	s_cbranch_scc0 .LBB0_1173
	v_add_u32_e32 v82, 0, v82
	v_add_u32_e32 v81, 0, v81
	v_add_u32_e32 v83, v82, v80
	v_add_u32_e32 v87, v81, v80
	s_waitcnt vmcnt(6)
	s_barrier
	ds_read_b128 v[64:67], v83
	ds_read_b128 v[68:71], v83 offset:4096
	ds_read_b128 v[72:75], v87 offset:32768
	ds_read_b128 v[88:91], v87 offset:36864
	v_add_u32_e32 v87, v82, v79
	v_add_u32_e32 v104, v81, v79
	ds_read_b128 v[92:95], v87
	ds_read_b128 v[96:99], v87 offset:4096
	ds_read_b128 v[100:103], v104 offset:32768
	ds_read_b128 v[104:107], v104 offset:36864
	s_waitcnt lgkmcnt(0)
	v_mfma_f32_32x32x16_bf16 v[48:63], v[64:67], v[72:75], v[48:63]
	v_add_u32_e32 v108, v82, v78
	v_mfma_f32_32x32x16_bf16 v[32:47], v[64:67], v[88:91], v[32:47]
	ds_read_b128 v[64:67], v108
	v_mfma_f32_32x32x16_bf16 v[16:31], v[68:71], v[72:75], v[16:31]
	v_mfma_f32_32x32x16_bf16 v[0:15], v[68:71], v[88:91], v[0:15]
	v_add_u32_e32 v88, v81, v78
	ds_read_b128 v[68:71], v88 offset:32768
	ds_read_b128 v[72:75], v108 offset:4096
	ds_read_b128 v[88:91], v88 offset:36864
	v_mfma_f32_32x32x16_bf16 v[48:63], v[92:95], v[100:103], v[48:63]
	v_add_u32_e32 v109, v82, v77
	v_add_u32_e32 v82, v81, v77
	v_mfma_f32_32x32x16_bf16 v[32:47], v[92:95], v[104:107], v[32:47]
	ds_read_b128 v[92:95], v109
	v_mfma_f32_32x32x16_bf16 v[16:31], v[96:99], v[100:103], v[16:31]
	v_mfma_f32_32x32x16_bf16 v[0:15], v[96:99], v[104:107], v[0:15]
	ds_read_b128 v[96:99], v82 offset:32768
	ds_read_b128 v[100:103], v109 offset:4096
	ds_read_b128 v[104:107], v82 offset:36864
	s_waitcnt lgkmcnt(0)
	v_mfma_f32_32x32x16_bf16 v[32:47], v[64:67], v[88:91], v[32:47]
	s_waitcnt vmcnt(0)
	s_barrier
	v_mfma_f32_32x32x16_bf16 v[0:15], v[72:75], v[88:91], v[0:15]
	v_mfma_f32_32x32x16_bf16 v[48:63], v[64:67], v[68:71], v[48:63]
	ds_read_b128 v[64:67], v83 offset:49152
	v_mfma_f32_32x32x16_bf16 v[16:31], v[72:75], v[68:71], v[16:31]
	v_mfma_f32_32x32x16_bf16 v[32:47], v[92:95], v[104:107], v[32:47]
	v_mfma_f32_32x32x16_bf16 v[0:15], v[100:103], v[104:107], v[0:15]
	v_add_u32_e32 v104, 0xc000, v81
	v_add_u32_e32 v80, v104, v80
	ds_read_b128 v[68:71], v80 offset:32768
	ds_read_b128 v[72:75], v83 offset:53248
	ds_read_b128 v[80:83], v80 offset:36864
	ds_read_b128 v[88:91], v87 offset:49152
	v_add_u32_e32 v79, v104, v79
	v_mfma_f32_32x32x16_bf16 v[48:63], v[92:95], v[96:99], v[48:63]
	v_mfma_f32_32x32x16_bf16 v[16:31], v[100:103], v[96:99], v[16:31]
	ds_read_b128 v[92:95], v79 offset:32768
	ds_read_b128 v[96:99], v87 offset:53248
	ds_read_b128 v[100:103], v79 offset:36864
	s_waitcnt lgkmcnt(0)
	v_mfma_f32_32x32x16_bf16 v[48:63], v[64:67], v[68:71], v[48:63]
	v_add_u32_e32 v78, v104, v78
	v_mfma_f32_32x32x16_bf16 v[32:47], v[64:67], v[80:83], v[32:47]
	ds_read_b128 v[64:67], v108 offset:49152
	v_mfma_f32_32x32x16_bf16 v[16:31], v[72:75], v[68:71], v[16:31]
	v_mfma_f32_32x32x16_bf16 v[0:15], v[72:75], v[80:83], v[0:15]
	ds_read_b128 v[68:71], v78 offset:32768
	ds_read_b128 v[72:75], v108 offset:53248
	ds_read_b128 v[78:81], v78 offset:36864
	v_mfma_f32_32x32x16_bf16 v[48:63], v[88:91], v[92:95], v[48:63]
	v_add_u32_e32 v77, v104, v77
	v_mfma_f32_32x32x16_bf16 v[32:47], v[88:91], v[100:103], v[32:47]
	ds_read_b128 v[88:91], v109 offset:49152
	v_mfma_f32_32x32x16_bf16 v[16:31], v[96:99], v[92:95], v[16:31]
	v_mfma_f32_32x32x16_bf16 v[0:15], v[96:99], v[100:103], v[0:15]
	ds_read_b128 v[92:95], v77 offset:32768
	ds_read_b128 v[96:99], v109 offset:53248
	ds_read_b128 v[100:103], v77 offset:36864
	s_waitcnt lgkmcnt(0)
	v_mfma_f32_32x32x16_bf16 v[48:63], v[64:67], v[68:71], v[48:63]
	s_waitcnt vmcnt(0)
	s_barrier
	v_mfma_f32_32x32x16_bf16 v[32:47], v[64:67], v[78:81], v[32:47]
	v_or3_b32 v64, s4, v84, v76
	v_lshlrev_b32_e32 v176, 2, v64
	global_load_dword v65, v176, s[58:59]
	v_add_u32_e32 v64, s6, v86
	v_or_b32_e32 v64, v64, v85
	v_mul_hi_i32 v66, v64, s35
	v_lshrrev_b32_e32 v67, 31, v66
	v_mfma_f32_32x32x16_bf16 v[16:31], v[72:75], v[68:71], v[16:31]
	v_ashrrev_i32_e32 v66, 11, v66
	v_add_u32_e32 v67, v66, v67
	v_mad_i32_i24 v70, v67, s33, v64
	v_lshlrev_b32_e32 v68, 13, v67
	v_cmp_lt_i32_e32 vcc, s82, v70
	v_add3_u32 v64, v68, v70, s79
	v_mfma_f32_32x32x16_bf16 v[0:15], v[72:75], v[78:81], v[0:15]
	v_mfma_f32_32x32x16_bf16 v[48:63], v[88:91], v[92:95], v[48:63]
	v_mfma_f32_32x32x16_bf16 v[32:47], v[88:91], v[100:103], v[32:47]
	v_mfma_f32_32x32x16_bf16 v[16:31], v[96:99], v[92:95], v[16:31]
	v_mfma_f32_32x32x16_bf16 v[0:15], v[96:99], v[100:103], v[0:15]
	s_load_dwordx2 s[92:93], s[0:1], 0xe8
	s_waitcnt lgkmcnt(0)
	s_and_saveexec_b64 s[2:3], vcc
	s_xor_b64 s[2:3], exec, s[2:3]
	s_mov_b64 s[4:5], s[92:93]
	v_add3_u32 v66, v68, v70, s79
	s_or_saveexec_b64 s[2:3], s[2:3]
	s_waitcnt lgkmcnt(0)
	v_mov_b64_e32 v[68:69], s[4:5]
	v_lshl_add_u32 v88, v67, 8, v70
	s_xor_b64 exec, exec, s[2:3]
	v_lshl_add_u32 v66, v67, 8, v70
	v_mov_b64_e32 v[68:69], s[64:65]
	s_or_b64 exec, exec, s[2:3]
	v_ashrrev_i32_e32 v67, 31, v66
	v_lshlrev_b64 v[66:67], 12, v[66:67]
	v_lshl_add_u64 v[66:67], v[68:69], 0, v[66:67]
	v_lshl_add_u64 v[66:67], v[66:67], 0, v[176:177]
	s_waitcnt vmcnt(0)
	v_mul_f32_e32 v48, v48, v65
	global_atomic_add_f32 v[66:67], v48, off
	v_or_b32_e32 v87, s6, v85
	v_add3_u32 v66, v86, v87, 1
	v_mul_hi_i32 v48, v66, s35
	v_lshrrev_b32_e32 v67, 31, v48
	v_ashrrev_i32_e32 v48, 11, v48
	v_add_u32_e32 v48, v48, v67
	v_mad_i32_i24 v69, v48, s33, v66
	v_lshlrev_b32_e32 v67, 13, v48
	v_cmp_lt_i32_e64 s[2:3], s82, v69
	v_add3_u32 v66, v67, v69, s79
	s_and_saveexec_b64 s[4:5], s[2:3]
	s_xor_b64 s[4:5], exec, s[4:5]
	s_mov_b64 s[6:7], s[92:93]
	v_add3_u32 v68, v67, v69, s79
	s_or_saveexec_b64 s[4:5], s[4:5]
	s_waitcnt lgkmcnt(0)
	v_mov_b64_e32 v[70:71], s[6:7]
	v_lshl_add_u32 v67, v48, 8, v69
	s_xor_b64 exec, exec, s[4:5]
	v_lshl_add_u32 v68, v48, 8, v69
	v_mov_b64_e32 v[70:71], s[64:65]
	s_or_b64 exec, exec, s[4:5]
	v_ashrrev_i32_e32 v69, 31, v68
	v_lshlrev_b64 v[68:69], 12, v[68:69]
	v_lshl_add_u64 v[68:69], v[70:71], 0, v[68:69]
	v_lshl_add_u64 v[68:69], v[68:69], 0, v[176:177]
	v_mul_f32_e32 v48, v49, v65
	global_atomic_add_f32 v[68:69], v48, off
	v_add3_u32 v48, v86, v87, 2
	v_mul_hi_i32 v49, v48, s35
	v_lshrrev_b32_e32 v68, 31, v49
	v_ashrrev_i32_e32 v49, 11, v49
	v_add_u32_e32 v49, v49, v68
	v_mad_i32_i24 v72, v49, s33, v48
	v_lshlrev_b32_e32 v69, 13, v49
	v_cmp_lt_i32_e64 s[4:5], s82, v72
	v_add3_u32 v68, v69, v72, s79
	s_and_saveexec_b64 s[6:7], s[4:5]
	s_xor_b64 s[6:7], exec, s[6:7]
	s_mov_b64 s[8:9], s[92:93]
	v_add3_u32 v48, v69, v72, s79
	s_or_saveexec_b64 s[6:7], s[6:7]
	s_waitcnt lgkmcnt(0)
	v_mov_b64_e32 v[70:71], s[8:9]
	v_lshl_add_u32 v69, v49, 8, v72
	s_xor_b64 exec, exec, s[6:7]
	v_lshl_add_u32 v48, v49, 8, v72
	v_mov_b64_e32 v[70:71], s[64:65]
	s_or_b64 exec, exec, s[6:7]
	v_ashrrev_i32_e32 v49, 31, v48
	v_lshlrev_b64 v[48:49], 12, v[48:49]
	v_lshl_add_u64 v[48:49], v[70:71], 0, v[48:49]
	v_lshl_add_u64 v[48:49], v[48:49], 0, v[176:177]
	v_mul_f32_e32 v50, v50, v65
	global_atomic_add_f32 v[48:49], v50, off
	v_add3_u32 v48, v86, v87, 3
	v_mul_hi_i32 v49, v48, s35
	v_lshrrev_b32_e32 v50, 31, v49
	v_ashrrev_i32_e32 v49, 11, v49
	v_add_u32_e32 v49, v49, v50
	v_mad_i32_i24 v72, v49, s33, v48
	v_lshlrev_b32_e32 v70, 13, v49
	v_cmp_lt_i32_e64 s[6:7], s82, v72
	v_add3_u32 v50, v70, v72, s79
	s_and_saveexec_b64 s[8:9], s[6:7]
	s_xor_b64 s[8:9], exec, s[8:9]
	s_mov_b64 s[10:11], s[92:93]
	v_add3_u32 v48, v70, v72, s79
	s_or_saveexec_b64 s[8:9], s[8:9]
	s_waitcnt lgkmcnt(0)
	v_mov_b64_e32 v[70:71], s[10:11]
	v_lshl_add_u32 v89, v49, 8, v72
	s_xor_b64 exec, exec, s[8:9]
	v_lshl_add_u32 v48, v49, 8, v72
	v_mov_b64_e32 v[70:71], s[64:65]
	s_or_b64 exec, exec, s[8:9]
	v_ashrrev_i32_e32 v49, 31, v48
	v_lshlrev_b64 v[48:49], 12, v[48:49]
	v_lshl_add_u64 v[48:49], v[70:71], 0, v[48:49]
	v_lshl_add_u64 v[48:49], v[48:49], 0, v[176:177]
	v_mul_f32_e32 v51, v51, v65
	global_atomic_add_f32 v[48:49], v51, off
	v_add3_u32 v48, v86, v87, 8
	v_mul_hi_i32 v49, v48, s35
	v_lshrrev_b32_e32 v51, 31, v49
	v_ashrrev_i32_e32 v49, 11, v49
	v_add_u32_e32 v49, v49, v51
	v_mad_i32_i24 v51, v49, s33, v48
	v_lshlrev_b32_e32 v71, 13, v49
	v_cmp_lt_i32_e64 s[8:9], s82, v51
	v_add3_u32 v70, v71, v51, s79
	s_and_saveexec_b64 s[10:11], s[8:9]
	s_xor_b64 s[10:11], exec, s[10:11]
	s_mov_b64 s[12:13], s[92:93]
	v_add3_u32 v48, v71, v51, s79
	s_or_saveexec_b64 s[10:11], s[10:11]
	s_waitcnt lgkmcnt(0)
	v_mov_b64_e32 v[72:73], s[12:13]
	v_lshl_add_u32 v71, v49, 8, v51
	s_xor_b64 exec, exec, s[10:11]
	v_lshl_add_u32 v48, v49, 8, v51
	v_mov_b64_e32 v[72:73], s[64:65]
	s_or_b64 exec, exec, s[10:11]
	v_ashrrev_i32_e32 v49, 31, v48
	v_lshlrev_b64 v[48:49], 12, v[48:49]
	v_lshl_add_u64 v[48:49], v[72:73], 0, v[48:49]
	v_lshl_add_u64 v[48:49], v[48:49], 0, v[176:177]
	v_mul_f32_e32 v51, v52, v65
	global_atomic_add_f32 v[48:49], v51, off
	v_add3_u32 v48, v86, v87, 9
	v_mul_hi_i32 v49, v48, s35
	v_lshrrev_b32_e32 v51, 31, v49
	v_ashrrev_i32_e32 v49, 11, v49
	v_add_u32_e32 v49, v49, v51
	v_mad_i32_i24 v51, v49, s33, v48
	v_lshlrev_b32_e32 v72, 13, v49
	v_cmp_lt_i32_e64 s[10:11], s82, v51
	v_add3_u32 v52, v72, v51, s79
	s_and_saveexec_b64 s[12:13], s[10:11]
	s_xor_b64 s[12:13], exec, s[12:13]
	s_mov_b64 s[14:15], s[92:93]
	v_add3_u32 v48, v72, v51, s79
	s_or_saveexec_b64 s[12:13], s[12:13]
	s_waitcnt lgkmcnt(0)
	v_mov_b64_e32 v[72:73], s[14:15]
	v_lshl_add_u32 v90, v49, 8, v51
	s_xor_b64 exec, exec, s[12:13]
	v_lshl_add_u32 v48, v49, 8, v51
	v_mov_b64_e32 v[72:73], s[64:65]
	s_or_b64 exec, exec, s[12:13]
	v_ashrrev_i32_e32 v49, 31, v48
	v_lshlrev_b64 v[48:49], 12, v[48:49]
	v_lshl_add_u64 v[48:49], v[72:73], 0, v[48:49]
	v_lshl_add_u64 v[48:49], v[48:49], 0, v[176:177]
	v_mul_f32_e32 v51, v53, v65
	global_atomic_add_f32 v[48:49], v51, off
	v_add3_u32 v48, v86, v87, 10
	v_mul_hi_i32 v49, v48, s35
	v_lshrrev_b32_e32 v51, 31, v49
	v_ashrrev_i32_e32 v49, 11, v49
	v_add_u32_e32 v49, v49, v51
	v_mad_i32_i24 v51, v49, s33, v48
	v_lshlrev_b32_e32 v53, 13, v49
	v_cmp_lt_i32_e64 s[12:13], s82, v51
	v_add3_u32 v72, v53, v51, s79
	s_and_saveexec_b64 s[14:15], s[12:13]
	s_xor_b64 s[14:15], exec, s[14:15]
	s_mov_b64 s[16:17], s[92:93]
	v_add3_u32 v48, v53, v51, s79
	s_or_saveexec_b64 s[14:15], s[14:15]
	s_waitcnt lgkmcnt(0)
	v_mov_b64_e32 v[74:75], s[16:17]
	v_lshl_add_u32 v73, v49, 8, v51
	s_xor_b64 exec, exec, s[14:15]
	v_lshl_add_u32 v48, v49, 8, v51
	v_mov_b64_e32 v[74:75], s[64:65]
	s_or_b64 exec, exec, s[14:15]
	v_ashrrev_i32_e32 v49, 31, v48
	v_lshlrev_b64 v[48:49], 12, v[48:49]
	v_lshl_add_u64 v[48:49], v[74:75], 0, v[48:49]
	v_lshl_add_u64 v[48:49], v[48:49], 0, v[176:177]
	v_mul_f32_e32 v51, v54, v65
	global_atomic_add_f32 v[48:49], v51, off
	v_add3_u32 v48, v86, v87, 11
	v_mul_hi_i32 v49, v48, s35
	v_lshrrev_b32_e32 v51, 31, v49
	v_ashrrev_i32_e32 v49, 11, v49
	v_add_u32_e32 v49, v49, v51
	v_mad_i32_i24 v51, v49, s33, v48
	v_lshlrev_b32_e32 v53, 13, v49
	v_cmp_lt_i32_e64 s[14:15], s82, v51
	v_add3_u32 v54, v53, v51, s79
	s_and_saveexec_b64 s[16:17], s[14:15]
	s_xor_b64 s[16:17], exec, s[16:17]
	s_mov_b64 s[18:19], s[92:93]
	v_add3_u32 v48, v53, v51, s79
	s_or_saveexec_b64 s[16:17], s[16:17]
	s_waitcnt lgkmcnt(0)
	v_mov_b64_e32 v[74:75], s[18:19]
	v_lshl_add_u32 v91, v49, 8, v51
	s_xor_b64 exec, exec, s[16:17]
	v_lshl_add_u32 v48, v49, 8, v51
	v_mov_b64_e32 v[74:75], s[64:65]
	s_or_b64 exec, exec, s[16:17]
	v_ashrrev_i32_e32 v49, 31, v48
	v_lshlrev_b64 v[48:49], 12, v[48:49]
	v_lshl_add_u64 v[48:49], v[74:75], 0, v[48:49]
	v_lshl_add_u64 v[48:49], v[48:49], 0, v[176:177]
	v_mul_f32_e32 v51, v55, v65
	global_atomic_add_f32 v[48:49], v51, off
	v_add3_u32 v48, v86, v87, 16
	v_mul_hi_i32 v49, v48, s35
	v_lshrrev_b32_e32 v51, 31, v49
	v_ashrrev_i32_e32 v49, 11, v49
	v_add_u32_e32 v49, v49, v51
	v_mad_i32_i24 v51, v49, s33, v48
	v_lshlrev_b32_e32 v53, 13, v49
	v_cmp_lt_i32_e64 s[16:17], s82, v51
	v_add3_u32 v74, v53, v51, s79
	s_and_saveexec_b64 s[18:19], s[16:17]
	s_xor_b64 s[18:19], exec, s[18:19]
	s_mov_b64 s[20:21], s[92:93]
	v_add3_u32 v48, v53, v51, s79
	s_or_saveexec_b64 s[18:19], s[18:19]
	s_waitcnt lgkmcnt(0)
	v_mov_b64_e32 v[76:77], s[20:21]
	v_lshl_add_u32 v75, v49, 8, v51
	s_xor_b64 exec, exec, s[18:19]
	v_lshl_add_u32 v48, v49, 8, v51
	v_mov_b64_e32 v[76:77], s[64:65]
	s_or_b64 exec, exec, s[18:19]
	v_ashrrev_i32_e32 v49, 31, v48
	v_lshlrev_b64 v[48:49], 12, v[48:49]
	v_lshl_add_u64 v[48:49], v[76:77], 0, v[48:49]
	v_lshl_add_u64 v[48:49], v[48:49], 0, v[176:177]
	v_mul_f32_e32 v51, v56, v65
	global_atomic_add_f32 v[48:49], v51, off
	v_add3_u32 v48, v86, v87, 17
	v_mul_hi_i32 v49, v48, s35
	v_lshrrev_b32_e32 v51, 31, v49
	v_ashrrev_i32_e32 v49, 11, v49
	v_add_u32_e32 v49, v49, v51
	v_mad_i32_i24 v51, v49, s33, v48
	v_lshlrev_b32_e32 v53, 13, v49
	v_cmp_lt_i32_e64 s[18:19], s82, v51
	v_add3_u32 v56, v53, v51, s79
	s_and_saveexec_b64 s[20:21], s[18:19]
	s_xor_b64 s[20:21], exec, s[20:21]
	s_mov_b64 s[22:23], s[92:93]
	v_add3_u32 v48, v53, v51, s79
	s_or_saveexec_b64 s[20:21], s[20:21]
	s_waitcnt lgkmcnt(0)
	v_mov_b64_e32 v[76:77], s[22:23]
	v_lshl_add_u32 v92, v49, 8, v51
	s_xor_b64 exec, exec, s[20:21]
	v_lshl_add_u32 v48, v49, 8, v51
	v_mov_b64_e32 v[76:77], s[64:65]
	s_or_b64 exec, exec, s[20:21]
	v_ashrrev_i32_e32 v49, 31, v48
	v_lshlrev_b64 v[48:49], 12, v[48:49]
	v_lshl_add_u64 v[48:49], v[76:77], 0, v[48:49]
	v_lshl_add_u64 v[48:49], v[48:49], 0, v[176:177]
	v_mul_f32_e32 v51, v57, v65
	global_atomic_add_f32 v[48:49], v51, off
	v_add3_u32 v48, v86, v87, 18
	v_mul_hi_i32 v49, v48, s35
	v_lshrrev_b32_e32 v51, 31, v49
	v_ashrrev_i32_e32 v49, 11, v49
	v_add_u32_e32 v49, v49, v51
	v_mad_i32_i24 v51, v49, s33, v48
	v_lshlrev_b32_e32 v53, 13, v49
	v_cmp_lt_i32_e64 s[20:21], s82, v51
	v_add3_u32 v76, v53, v51, s79
	s_and_saveexec_b64 s[22:23], s[20:21]
	s_xor_b64 s[22:23], exec, s[22:23]
	s_mov_b64 s[24:25], s[92:93]
	v_add3_u32 v48, v53, v51, s79
	s_or_saveexec_b64 s[22:23], s[22:23]
	s_waitcnt lgkmcnt(0)
	v_mov_b64_e32 v[78:79], s[24:25]
	v_lshl_add_u32 v77, v49, 8, v51
	s_xor_b64 exec, exec, s[22:23]
	v_lshl_add_u32 v48, v49, 8, v51
	v_mov_b64_e32 v[78:79], s[64:65]
	s_or_b64 exec, exec, s[22:23]
	v_ashrrev_i32_e32 v49, 31, v48
	v_lshlrev_b64 v[48:49], 12, v[48:49]
	v_lshl_add_u64 v[48:49], v[78:79], 0, v[48:49]
	v_lshl_add_u64 v[48:49], v[48:49], 0, v[176:177]
	v_mul_f32_e32 v51, v58, v65
	global_atomic_add_f32 v[48:49], v51, off
	v_add3_u32 v48, v86, v87, 19
	v_mul_hi_i32 v49, v48, s35
	v_lshrrev_b32_e32 v51, 31, v49
	v_ashrrev_i32_e32 v49, 11, v49
	v_add_u32_e32 v49, v49, v51
	v_mad_i32_i24 v51, v49, s33, v48
	v_lshlrev_b32_e32 v53, 13, v49
	v_cmp_lt_i32_e64 s[22:23], s82, v51
	v_add3_u32 v58, v53, v51, s79
	s_and_saveexec_b64 s[24:25], s[22:23]
	s_xor_b64 s[24:25], exec, s[24:25]
	s_mov_b64 s[26:27], s[92:93]
	v_add3_u32 v48, v53, v51, s79
	s_or_saveexec_b64 s[24:25], s[24:25]
	s_waitcnt lgkmcnt(0)
	v_mov_b64_e32 v[78:79], s[26:27]
	v_lshl_add_u32 v93, v49, 8, v51
	s_xor_b64 exec, exec, s[24:25]
	v_lshl_add_u32 v48, v49, 8, v51
	v_mov_b64_e32 v[78:79], s[64:65]
	s_or_b64 exec, exec, s[24:25]
	v_ashrrev_i32_e32 v49, 31, v48
	v_lshlrev_b64 v[48:49], 12, v[48:49]
	v_lshl_add_u64 v[48:49], v[78:79], 0, v[48:49]
	v_lshl_add_u64 v[48:49], v[48:49], 0, v[176:177]
	v_mul_f32_e32 v51, v59, v65
	global_atomic_add_f32 v[48:49], v51, off
	v_add3_u32 v48, v86, v87, 24
	v_mul_hi_i32 v49, v48, s35
	v_lshrrev_b32_e32 v51, 31, v49
	v_ashrrev_i32_e32 v49, 11, v49
	v_add_u32_e32 v49, v49, v51
	v_mad_i32_i24 v51, v49, s33, v48
	v_lshlrev_b32_e32 v53, 13, v49
	v_cmp_lt_i32_e64 s[24:25], s82, v51
	v_add3_u32 v78, v53, v51, s79
	s_and_saveexec_b64 s[26:27], s[24:25]
	s_xor_b64 s[26:27], exec, s[26:27]
	s_mov_b64 s[28:29], s[92:93]
	v_add3_u32 v48, v53, v51, s79
	s_or_saveexec_b64 s[26:27], s[26:27]
	s_waitcnt lgkmcnt(0)
	v_mov_b64_e32 v[80:81], s[28:29]
	v_lshl_add_u32 v79, v49, 8, v51
	s_xor_b64 exec, exec, s[26:27]
	v_lshl_add_u32 v48, v49, 8, v51
	v_mov_b64_e32 v[80:81], s[64:65]
	s_or_b64 exec, exec, s[26:27]
	v_ashrrev_i32_e32 v49, 31, v48
	v_lshlrev_b64 v[48:49], 12, v[48:49]
	v_lshl_add_u64 v[48:49], v[80:81], 0, v[48:49]
	v_lshl_add_u64 v[48:49], v[48:49], 0, v[176:177]
	v_mul_f32_e32 v51, v60, v65
	global_atomic_add_f32 v[48:49], v51, off
	v_add3_u32 v48, v86, v87, 25
	v_mul_hi_i32 v49, v48, s35
	v_lshrrev_b32_e32 v51, 31, v49
	v_ashrrev_i32_e32 v49, 11, v49
	v_add_u32_e32 v49, v49, v51
	v_mad_i32_i24 v51, v49, s33, v48
	v_lshlrev_b32_e32 v53, 13, v49
	v_cmp_lt_i32_e64 s[26:27], s82, v51
	v_add3_u32 v60, v53, v51, s79
	s_and_saveexec_b64 s[28:29], s[26:27]
	s_xor_b64 s[28:29], exec, s[28:29]
	s_mov_b64 s[30:31], s[92:93]
	v_add3_u32 v48, v53, v51, s79
	s_or_saveexec_b64 s[28:29], s[28:29]
	s_waitcnt lgkmcnt(0)
	v_mov_b64_e32 v[80:81], s[30:31]
	v_lshl_add_u32 v94, v49, 8, v51
	s_xor_b64 exec, exec, s[28:29]
	v_lshl_add_u32 v48, v49, 8, v51
	v_mov_b64_e32 v[80:81], s[64:65]
	s_or_b64 exec, exec, s[28:29]
	v_ashrrev_i32_e32 v49, 31, v48
	v_lshlrev_b64 v[48:49], 12, v[48:49]
	v_lshl_add_u64 v[48:49], v[80:81], 0, v[48:49]
	v_lshl_add_u64 v[48:49], v[48:49], 0, v[176:177]
	v_mul_f32_e32 v51, v61, v65
	global_atomic_add_f32 v[48:49], v51, off
	v_add3_u32 v48, v86, v87, 26
	v_mul_hi_i32 v49, v48, s35
	v_lshrrev_b32_e32 v51, 31, v49
	v_ashrrev_i32_e32 v49, 11, v49
	v_add_u32_e32 v49, v49, v51
	v_mad_i32_i24 v51, v49, s33, v48
	v_lshlrev_b32_e32 v53, 13, v49
	v_cmp_lt_i32_e64 s[28:29], s82, v51
	v_add3_u32 v80, v53, v51, s79
	s_and_saveexec_b64 s[30:31], s[28:29]
	s_xor_b64 s[30:31], exec, s[30:31]
	s_mov_b64 s[74:75], s[92:93]
	v_add3_u32 v48, v53, v51, s79
	s_or_saveexec_b64 s[30:31], s[30:31]
	s_waitcnt lgkmcnt(0)
	v_mov_b64_e32 v[82:83], s[74:75]
	v_lshl_add_u32 v81, v49, 8, v51
	s_xor_b64 exec, exec, s[30:31]
	v_lshl_add_u32 v48, v49, 8, v51
	v_mov_b64_e32 v[82:83], s[64:65]
	s_or_b64 exec, exec, s[30:31]
	v_ashrrev_i32_e32 v49, 31, v48
	v_lshlrev_b64 v[48:49], 12, v[48:49]
	v_lshl_add_u64 v[48:49], v[82:83], 0, v[48:49]
	v_lshl_add_u64 v[48:49], v[48:49], 0, v[176:177]
	v_mul_f32_e32 v51, v62, v65
	global_atomic_add_f32 v[48:49], v51, off
	v_add3_u32 v48, v86, v87, 27
	v_mul_hi_i32 v49, v48, s35
	v_lshrrev_b32_e32 v51, 31, v49
	v_ashrrev_i32_e32 v49, 11, v49
	v_add_u32_e32 v49, v49, v51
	v_mad_i32_i24 v51, v49, s33, v48
	v_lshlrev_b32_e32 v53, 13, v49
	v_cmp_lt_i32_e64 s[30:31], s82, v51
	v_add3_u32 v62, v53, v51, s79
	s_and_saveexec_b64 s[74:75], s[30:31]
	s_xor_b64 s[74:75], exec, s[74:75]
	s_mov_b64 s[76:77], s[92:93]
	v_add3_u32 v48, v53, v51, s79
	s_or_saveexec_b64 s[74:75], s[74:75]
	s_waitcnt lgkmcnt(0)
	v_mov_b64_e32 v[82:83], s[76:77]
	v_lshl_add_u32 v95, v49, 8, v51
	s_xor_b64 exec, exec, s[74:75]
	v_lshl_add_u32 v48, v49, 8, v51
	v_mov_b64_e32 v[82:83], s[64:65]
	s_or_b64 exec, exec, s[74:75]
	v_ashrrev_i32_e32 v49, 31, v48
	v_lshlrev_b64 v[48:49], 12, v[48:49]
	v_lshl_add_u64 v[48:49], v[82:83], 0, v[48:49]
	v_lshl_add_u64 v[48:49], v[48:49], 0, v[176:177]
	v_mul_f32_e32 v51, v63, v65
	global_atomic_add_f32 v[48:49], v51, off
	v_or_b32_e32 v48, 0x80, v176
	global_load_dword v49, v48, s[58:59]
	s_and_saveexec_b64 s[74:75], vcc
	s_xor_b64 s[74:75], exec, s[74:75]
	s_mov_b64 s[76:77], s[92:93]
	s_or_saveexec_b64 s[74:75], s[74:75]
	s_waitcnt lgkmcnt(0)
	v_mov_b64_e32 v[82:83], s[76:77]
	s_xor_b64 exec, exec, s[74:75]
	v_mov_b64_e32 v[82:83], s[64:65]
	v_mov_b32_e32 v64, v88
	s_or_b64 exec, exec, s[74:75]
	v_ashrrev_i32_e32 v65, 31, v64
	v_lshlrev_b64 v[64:65], 12, v[64:65]
	v_lshl_add_u64 v[64:65], v[82:83], 0, v[64:65]
	v_lshl_add_u64 v[64:65], v[64:65], 0, v[176:177]
	s_waitcnt vmcnt(0)
	v_mul_f32_e32 v32, v32, v49
	global_atomic_add_f32 v[64:65], v32, off offset:128
	s_and_saveexec_b64 s[76:77], s[2:3]
	s_xor_b64 s[2:3], exec, s[76:77]
	s_mov_b64 s[74:75], s[92:93]
	s_or_saveexec_b64 s[2:3], s[2:3]
	s_waitcnt lgkmcnt(0)
	v_mov_b64_e32 v[64:65], s[74:75]
	s_xor_b64 exec, exec, s[2:3]
	v_mov_b64_e32 v[64:65], s[64:65]
	v_mov_b32_e32 v66, v67
	s_or_b64 exec, exec, s[2:3]
	v_ashrrev_i32_e32 v67, 31, v66
	v_lshlrev_b64 v[66:67], 12, v[66:67]
	v_lshl_add_u64 v[64:65], v[64:65], 0, v[66:67]
	v_lshl_add_u64 v[64:65], v[64:65], 0, v[176:177]
	v_mul_f32_e32 v32, v33, v49
	global_atomic_add_f32 v[64:65], v32, off offset:128
	s_and_saveexec_b64 s[2:3], s[4:5]
	s_xor_b64 s[2:3], exec, s[2:3]
	s_mov_b64 s[74:75], s[92:93]
	s_or_saveexec_b64 s[2:3], s[2:3]
	s_waitcnt lgkmcnt(0)
	v_mov_b64_e32 v[32:33], s[74:75]
	s_xor_b64 exec, exec, s[2:3]
	v_mov_b64_e32 v[32:33], s[64:65]
	v_mov_b32_e32 v68, v69
	s_or_b64 exec, exec, s[2:3]
	v_ashrrev_i32_e32 v69, 31, v68
	v_lshlrev_b64 v[64:65], 12, v[68:69]
	v_lshl_add_u64 v[32:33], v[32:33], 0, v[64:65]
	v_lshl_add_u64 v[32:33], v[32:33], 0, v[176:177]
	v_mul_f32_e32 v34, v34, v49
	global_atomic_add_f32 v[32:33], v34, off offset:128
	s_and_saveexec_b64 s[2:3], s[6:7]
	s_xor_b64 s[2:3], exec, s[2:3]
	s_mov_b64 s[4:5], s[92:93]
	s_or_saveexec_b64 s[2:3], s[2:3]
	s_waitcnt lgkmcnt(0)
	v_mov_b64_e32 v[32:33], s[4:5]
	s_xor_b64 exec, exec, s[2:3]
	v_mov_b64_e32 v[32:33], s[64:65]
	v_mov_b32_e32 v50, v89
	s_or_b64 exec, exec, s[2:3]
	v_ashrrev_i32_e32 v51, 31, v50
	v_lshlrev_b64 v[50:51], 12, v[50:51]
	v_lshl_add_u64 v[32:33], v[32:33], 0, v[50:51]
	v_lshl_add_u64 v[32:33], v[32:33], 0, v[176:177]
	v_mul_f32_e32 v34, v35, v49
	global_atomic_add_f32 v[32:33], v34, off offset:128
	s_and_saveexec_b64 s[2:3], s[8:9]
	s_xor_b64 s[2:3], exec, s[2:3]
	s_mov_b64 s[4:5], s[92:93]
	s_or_saveexec_b64 s[2:3], s[2:3]
	s_waitcnt lgkmcnt(0)
	v_mov_b64_e32 v[32:33], s[4:5]
	s_xor_b64 exec, exec, s[2:3]
	v_mov_b64_e32 v[32:33], s[64:65]
	v_mov_b32_e32 v70, v71
	s_or_b64 exec, exec, s[2:3]
	v_ashrrev_i32_e32 v71, 31, v70
	v_lshlrev_b64 v[34:35], 12, v[70:71]
	v_lshl_add_u64 v[32:33], v[32:33], 0, v[34:35]
	v_lshl_add_u64 v[32:33], v[32:33], 0, v[176:177]
	v_mul_f32_e32 v34, v36, v49
	global_atomic_add_f32 v[32:33], v34, off offset:128
	s_and_saveexec_b64 s[2:3], s[10:11]
	s_xor_b64 s[2:3], exec, s[2:3]
	s_mov_b64 s[4:5], s[92:93]
	s_or_saveexec_b64 s[2:3], s[2:3]
	s_waitcnt lgkmcnt(0)
	v_mov_b64_e32 v[32:33], s[4:5]
	s_xor_b64 exec, exec, s[2:3]
	v_mov_b64_e32 v[32:33], s[64:65]
	v_mov_b32_e32 v52, v90
	s_or_b64 exec, exec, s[2:3]
	v_ashrrev_i32_e32 v53, 31, v52
	v_lshlrev_b64 v[34:35], 12, v[52:53]
	v_lshl_add_u64 v[32:33], v[32:33], 0, v[34:35]
	v_lshl_add_u64 v[32:33], v[32:33], 0, v[176:177]
	v_mul_f32_e32 v34, v37, v49
	global_atomic_add_f32 v[32:33], v34, off offset:128
	s_and_saveexec_b64 s[2:3], s[12:13]
	s_xor_b64 s[2:3], exec, s[2:3]
	s_mov_b64 s[4:5], s[92:93]
	s_or_saveexec_b64 s[2:3], s[2:3]
	s_waitcnt lgkmcnt(0)
	v_mov_b64_e32 v[32:33], s[4:5]
	s_xor_b64 exec, exec, s[2:3]
	v_mov_b64_e32 v[32:33], s[64:65]
	v_mov_b32_e32 v72, v73
	s_or_b64 exec, exec, s[2:3]
	v_ashrrev_i32_e32 v73, 31, v72
	v_lshlrev_b64 v[34:35], 12, v[72:73]
	v_lshl_add_u64 v[32:33], v[32:33], 0, v[34:35]
	v_lshl_add_u64 v[32:33], v[32:33], 0, v[176:177]
	v_mul_f32_e32 v34, v38, v49
	global_atomic_add_f32 v[32:33], v34, off offset:128
	s_and_saveexec_b64 s[2:3], s[14:15]
	s_xor_b64 s[2:3], exec, s[2:3]
	s_mov_b64 s[4:5], s[92:93]
	s_or_saveexec_b64 s[2:3], s[2:3]
	s_waitcnt lgkmcnt(0)
	v_mov_b64_e32 v[32:33], s[4:5]
	s_xor_b64 exec, exec, s[2:3]
	v_mov_b64_e32 v[32:33], s[64:65]
	v_mov_b32_e32 v54, v91
	s_or_b64 exec, exec, s[2:3]
	v_ashrrev_i32_e32 v55, 31, v54
	v_lshlrev_b64 v[34:35], 12, v[54:55]
	v_lshl_add_u64 v[32:33], v[32:33], 0, v[34:35]
	v_lshl_add_u64 v[32:33], v[32:33], 0, v[176:177]
	v_mul_f32_e32 v34, v39, v49
	global_atomic_add_f32 v[32:33], v34, off offset:128
	s_and_saveexec_b64 s[2:3], s[16:17]
	s_xor_b64 s[2:3], exec, s[2:3]
	s_mov_b64 s[4:5], s[92:93]
	s_or_saveexec_b64 s[2:3], s[2:3]
	s_waitcnt lgkmcnt(0)
	v_mov_b64_e32 v[32:33], s[4:5]
	s_xor_b64 exec, exec, s[2:3]
	v_mov_b64_e32 v[32:33], s[64:65]
	v_mov_b32_e32 v74, v75
	s_or_b64 exec, exec, s[2:3]
	v_ashrrev_i32_e32 v75, 31, v74
	v_lshlrev_b64 v[34:35], 12, v[74:75]
	v_lshl_add_u64 v[32:33], v[32:33], 0, v[34:35]
	v_lshl_add_u64 v[32:33], v[32:33], 0, v[176:177]
	v_mul_f32_e32 v34, v40, v49
	global_atomic_add_f32 v[32:33], v34, off offset:128
	s_and_saveexec_b64 s[2:3], s[18:19]
	s_xor_b64 s[2:3], exec, s[2:3]
	s_mov_b64 s[4:5], s[92:93]
	s_or_saveexec_b64 s[2:3], s[2:3]
	s_waitcnt lgkmcnt(0)
	v_mov_b64_e32 v[32:33], s[4:5]
	s_xor_b64 exec, exec, s[2:3]
	v_mov_b64_e32 v[32:33], s[64:65]
	v_mov_b32_e32 v56, v92
	s_or_b64 exec, exec, s[2:3]
	v_ashrrev_i32_e32 v57, 31, v56
	v_lshlrev_b64 v[34:35], 12, v[56:57]
	v_lshl_add_u64 v[32:33], v[32:33], 0, v[34:35]
	v_lshl_add_u64 v[32:33], v[32:33], 0, v[176:177]
	v_mul_f32_e32 v34, v41, v49
	global_atomic_add_f32 v[32:33], v34, off offset:128
	s_and_saveexec_b64 s[2:3], s[20:21]
	s_xor_b64 s[2:3], exec, s[2:3]
	s_mov_b64 s[4:5], s[92:93]
	s_or_saveexec_b64 s[2:3], s[2:3]
	s_waitcnt lgkmcnt(0)
	v_mov_b64_e32 v[32:33], s[4:5]
	s_xor_b64 exec, exec, s[2:3]
	v_mov_b64_e32 v[32:33], s[64:65]
	v_mov_b32_e32 v76, v77
	s_or_b64 exec, exec, s[2:3]
	v_ashrrev_i32_e32 v77, 31, v76
	v_lshlrev_b64 v[34:35], 12, v[76:77]
	v_lshl_add_u64 v[32:33], v[32:33], 0, v[34:35]
	v_lshl_add_u64 v[32:33], v[32:33], 0, v[176:177]
	v_mul_f32_e32 v34, v42, v49
	global_atomic_add_f32 v[32:33], v34, off offset:128
	s_and_saveexec_b64 s[2:3], s[22:23]
	s_xor_b64 s[2:3], exec, s[2:3]
	s_mov_b64 s[4:5], s[92:93]
	s_or_saveexec_b64 s[2:3], s[2:3]
	s_waitcnt lgkmcnt(0)
	v_mov_b64_e32 v[32:33], s[4:5]
	s_xor_b64 exec, exec, s[2:3]
	v_mov_b64_e32 v[32:33], s[64:65]
	v_mov_b32_e32 v58, v93
	s_or_b64 exec, exec, s[2:3]
	v_ashrrev_i32_e32 v59, 31, v58
	v_lshlrev_b64 v[34:35], 12, v[58:59]
	v_lshl_add_u64 v[32:33], v[32:33], 0, v[34:35]
	v_lshl_add_u64 v[32:33], v[32:33], 0, v[176:177]
	v_mul_f32_e32 v34, v43, v49
	global_atomic_add_f32 v[32:33], v34, off offset:128
	s_and_saveexec_b64 s[2:3], s[24:25]
	s_xor_b64 s[2:3], exec, s[2:3]
	s_mov_b64 s[4:5], s[92:93]
	s_or_saveexec_b64 s[2:3], s[2:3]
	s_waitcnt lgkmcnt(0)
	v_mov_b64_e32 v[32:33], s[4:5]
	s_xor_b64 exec, exec, s[2:3]
	v_mov_b64_e32 v[32:33], s[64:65]
	v_mov_b32_e32 v78, v79
	s_or_b64 exec, exec, s[2:3]
	v_ashrrev_i32_e32 v79, 31, v78
	v_lshlrev_b64 v[34:35], 12, v[78:79]
	v_lshl_add_u64 v[32:33], v[32:33], 0, v[34:35]
	v_lshl_add_u64 v[32:33], v[32:33], 0, v[176:177]
	v_mul_f32_e32 v34, v44, v49
	global_atomic_add_f32 v[32:33], v34, off offset:128
	s_and_saveexec_b64 s[2:3], s[26:27]
	s_xor_b64 s[2:3], exec, s[2:3]
	s_mov_b64 s[4:5], s[92:93]
	s_or_saveexec_b64 s[2:3], s[2:3]
	s_waitcnt lgkmcnt(0)
	v_mov_b64_e32 v[32:33], s[4:5]
	s_xor_b64 exec, exec, s[2:3]
	v_mov_b64_e32 v[32:33], s[64:65]
	v_mov_b32_e32 v60, v94
	s_or_b64 exec, exec, s[2:3]
	v_ashrrev_i32_e32 v61, 31, v60
	v_lshlrev_b64 v[34:35], 12, v[60:61]
	v_lshl_add_u64 v[32:33], v[32:33], 0, v[34:35]
	v_lshl_add_u64 v[32:33], v[32:33], 0, v[176:177]
	v_mul_f32_e32 v34, v45, v49
	global_atomic_add_f32 v[32:33], v34, off offset:128
	s_and_saveexec_b64 s[2:3], s[28:29]
	s_xor_b64 s[2:3], exec, s[2:3]
	s_mov_b64 s[4:5], s[92:93]
	s_or_saveexec_b64 s[2:3], s[2:3]
	s_waitcnt lgkmcnt(0)
	v_mov_b64_e32 v[32:33], s[4:5]
	s_xor_b64 exec, exec, s[2:3]
	v_mov_b64_e32 v[32:33], s[64:65]
	v_mov_b32_e32 v80, v81
	s_or_b64 exec, exec, s[2:3]
	v_ashrrev_i32_e32 v81, 31, v80
	v_lshlrev_b64 v[34:35], 12, v[80:81]
	v_lshl_add_u64 v[32:33], v[32:33], 0, v[34:35]
	v_lshl_add_u64 v[32:33], v[32:33], 0, v[176:177]
	v_mul_f32_e32 v34, v46, v49
	global_atomic_add_f32 v[32:33], v34, off offset:128
	s_and_saveexec_b64 s[2:3], s[30:31]
	s_xor_b64 s[2:3], exec, s[2:3]
	s_mov_b64 s[4:5], s[92:93]
	s_or_saveexec_b64 s[2:3], s[2:3]
	s_waitcnt lgkmcnt(0)
	v_mov_b64_e32 v[32:33], s[4:5]
	s_xor_b64 exec, exec, s[2:3]
	v_mov_b64_e32 v[32:33], s[64:65]
	v_mov_b32_e32 v62, v95
	s_or_b64 exec, exec, s[2:3]
	v_ashrrev_i32_e32 v63, 31, v62
	v_lshlrev_b64 v[36:37], 12, v[62:63]
	v_lshl_add_u64 v[32:33], v[32:33], 0, v[36:37]
	v_lshl_add_u64 v[32:33], v[32:33], 0, v[176:177]
	v_mul_f32_e32 v36, v47, v49
	v_lshl_add_u64 v[34:35], s[58:59], 0, v[176:177]
	global_atomic_add_f32 v[32:33], v36, off offset:128
	global_load_dword v54, v[34:35], off
	v_add3_u32 v32, v86, v87, 32
	v_mul_hi_i32 v33, v32, s35
	v_lshrrev_b32_e32 v34, 31, v33
	v_ashrrev_i32_e32 v33, 11, v33
	v_add_u32_e32 v35, v33, v34
	v_mad_i32_i24 v38, v35, s33, v32
	v_lshlrev_b32_e32 v33, 13, v35
	v_cmp_lt_i32_e32 vcc, s82, v38
	v_add3_u32 v32, v33, v38, s79
	s_and_saveexec_b64 s[2:3], vcc
	s_xor_b64 s[2:3], exec, s[2:3]
	s_mov_b64 s[4:5], s[92:93]
	v_add3_u32 v34, v33, v38, s79
	s_or_saveexec_b64 s[2:3], s[2:3]
	s_waitcnt lgkmcnt(0)
	v_mov_b64_e32 v[36:37], s[4:5]
	v_lshl_add_u32 v33, v35, 8, v38
	s_xor_b64 exec, exec, s[2:3]
	v_lshl_add_u32 v34, v35, 8, v38
	v_mov_b64_e32 v[36:37], s[64:65]
	s_or_b64 exec, exec, s[2:3]
	v_ashrrev_i32_e32 v35, 31, v34
	v_lshlrev_b64 v[34:35], 12, v[34:35]
	v_lshl_add_u64 v[34:35], v[36:37], 0, v[34:35]
	v_lshl_add_u64 v[34:35], v[34:35], 0, v[176:177]
	s_waitcnt vmcnt(0)
	v_mul_f32_e32 v16, v16, v54
	global_atomic_add_f32 v[34:35], v16, off
	v_add3_u32 v16, v86, v87, 33
	v_mul_hi_i32 v34, v16, s35
	v_lshrrev_b32_e32 v35, 31, v34
	v_ashrrev_i32_e32 v34, 11, v34
	v_add_u32_e32 v35, v34, v35
	v_mad_i32_i24 v38, v35, s33, v16
	v_lshlrev_b32_e32 v36, 13, v35
	v_cmp_lt_i32_e64 s[2:3], s82, v38
	v_add3_u32 v16, v36, v38, s79
	s_and_saveexec_b64 s[4:5], s[2:3]
	s_xor_b64 s[4:5], exec, s[4:5]
	s_mov_b64 s[6:7], s[92:93]
	v_add3_u32 v34, v36, v38, s79
	s_or_saveexec_b64 s[4:5], s[4:5]
	s_waitcnt lgkmcnt(0)
	v_mov_b64_e32 v[36:37], s[6:7]
	v_lshl_add_u32 v55, v35, 8, v38
	s_xor_b64 exec, exec, s[4:5]
	v_lshl_add_u32 v34, v35, 8, v38
	v_mov_b64_e32 v[36:37], s[64:65]
	s_or_b64 exec, exec, s[4:5]
	v_ashrrev_i32_e32 v35, 31, v34
	v_lshlrev_b64 v[34:35], 12, v[34:35]
	v_lshl_add_u64 v[34:35], v[36:37], 0, v[34:35]
	v_lshl_add_u64 v[34:35], v[34:35], 0, v[176:177]
	v_mul_f32_e32 v17, v17, v54
	global_atomic_add_f32 v[34:35], v17, off
	v_add3_u32 v34, v86, v87, 34
	v_mul_hi_i32 v17, v34, s35
	v_lshrrev_b32_e32 v35, 31, v17
	v_ashrrev_i32_e32 v17, 11, v17
	v_add_u32_e32 v17, v17, v35
	v_mad_i32_i24 v37, v17, s33, v34
	v_lshlrev_b32_e32 v35, 13, v17
	v_cmp_lt_i32_e64 s[4:5], s82, v37
	v_add3_u32 v34, v35, v37, s79
	s_and_saveexec_b64 s[6:7], s[4:5]
	s_xor_b64 s[6:7], exec, s[6:7]
	s_mov_b64 s[8:9], s[92:93]
	v_add3_u32 v36, v35, v37, s79
	s_or_saveexec_b64 s[6:7], s[6:7]
	s_waitcnt lgkmcnt(0)
	v_mov_b64_e32 v[38:39], s[8:9]
	v_lshl_add_u32 v35, v17, 8, v37
	s_xor_b64 exec, exec, s[6:7]
	v_lshl_add_u32 v36, v17, 8, v37
	v_mov_b64_e32 v[38:39], s[64:65]
	s_or_b64 exec, exec, s[6:7]
	v_ashrrev_i32_e32 v37, 31, v36
	v_lshlrev_b64 v[36:37], 12, v[36:37]
	v_lshl_add_u64 v[36:37], v[38:39], 0, v[36:37]
	v_lshl_add_u64 v[36:37], v[36:37], 0, v[176:177]
	v_mul_f32_e32 v17, v18, v54
	global_atomic_add_f32 v[36:37], v17, off
	v_add3_u32 v18, v86, v87, 35
	v_mul_hi_i32 v17, v18, s35
	v_lshrrev_b32_e32 v36, 31, v17
	v_ashrrev_i32_e32 v17, 11, v17
	v_add_u32_e32 v17, v17, v36
	v_mad_i32_i24 v37, v17, s33, v18
	v_lshlrev_b32_e32 v38, 13, v17
	v_cmp_lt_i32_e64 s[6:7], s82, v37
	v_add3_u32 v18, v38, v37, s79
	s_and_saveexec_b64 s[8:9], s[6:7]
	s_xor_b64 s[8:9], exec, s[8:9]
	s_mov_b64 s[10:11], s[92:93]
	v_add3_u32 v36, v38, v37, s79
	s_or_saveexec_b64 s[8:9], s[8:9]
	s_waitcnt lgkmcnt(0)
	v_mov_b64_e32 v[38:39], s[10:11]
	v_lshl_add_u32 v56, v17, 8, v37
	s_xor_b64 exec, exec, s[8:9]
	v_lshl_add_u32 v36, v17, 8, v37
	v_mov_b64_e32 v[38:39], s[64:65]
	s_or_b64 exec, exec, s[8:9]
	v_ashrrev_i32_e32 v37, 31, v36
	v_lshlrev_b64 v[36:37], 12, v[36:37]
	v_lshl_add_u64 v[36:37], v[38:39], 0, v[36:37]
	v_lshl_add_u64 v[36:37], v[36:37], 0, v[176:177]
	v_mul_f32_e32 v17, v19, v54
	global_atomic_add_f32 v[36:37], v17, off
	v_add3_u32 v19, v86, v87, 40
	v_mul_hi_i32 v17, v19, s35
	v_lshrrev_b32_e32 v36, 31, v17
	v_ashrrev_i32_e32 v17, 11, v17
	v_add_u32_e32 v17, v17, v36
	v_mad_i32_i24 v19, v17, s33, v19
	v_lshlrev_b32_e32 v37, 13, v17
	v_cmp_lt_i32_e64 s[8:9], s82, v19
	v_add3_u32 v36, v37, v19, s79
	s_and_saveexec_b64 s[10:11], s[8:9]
	s_xor_b64 s[10:11], exec, s[10:11]
	s_mov_b64 s[12:13], s[92:93]
	v_add3_u32 v38, v37, v19, s79
	s_or_saveexec_b64 s[10:11], s[10:11]
	s_waitcnt lgkmcnt(0)
	v_mov_b64_e32 v[40:41], s[12:13]
	v_lshl_add_u32 v37, v17, 8, v19
	s_xor_b64 exec, exec, s[10:11]
	v_lshl_add_u32 v38, v17, 8, v19
	v_mov_b64_e32 v[40:41], s[64:65]
	s_or_b64 exec, exec, s[10:11]
	v_ashrrev_i32_e32 v39, 31, v38
	v_lshlrev_b64 v[38:39], 12, v[38:39]
	v_lshl_add_u64 v[38:39], v[40:41], 0, v[38:39]
	v_lshl_add_u64 v[38:39], v[38:39], 0, v[176:177]
	v_mul_f32_e32 v17, v20, v54
	global_atomic_add_f32 v[38:39], v17, off
	v_add3_u32 v19, v86, v87, 41
	v_mul_hi_i32 v17, v19, s35
	v_lshrrev_b32_e32 v20, 31, v17
	v_ashrrev_i32_e32 v17, 11, v17
	v_add_u32_e32 v17, v17, v20
	v_mad_i32_i24 v19, v17, s33, v19
	v_lshlrev_b32_e32 v39, 13, v17
	v_cmp_lt_i32_e64 s[10:11], s82, v19
	v_add3_u32 v20, v39, v19, s79
	s_and_saveexec_b64 s[12:13], s[10:11]
	s_xor_b64 s[12:13], exec, s[12:13]
	s_mov_b64 s[14:15], s[92:93]
	v_add3_u32 v38, v39, v19, s79
	s_or_saveexec_b64 s[12:13], s[12:13]
	s_waitcnt lgkmcnt(0)
	v_mov_b64_e32 v[40:41], s[14:15]
	v_lshl_add_u32 v57, v17, 8, v19
	s_xor_b64 exec, exec, s[12:13]
	v_lshl_add_u32 v38, v17, 8, v19
	v_mov_b64_e32 v[40:41], s[64:65]
	s_or_b64 exec, exec, s[12:13]
	v_ashrrev_i32_e32 v39, 31, v38
	v_lshlrev_b64 v[38:39], 12, v[38:39]
	v_lshl_add_u64 v[38:39], v[40:41], 0, v[38:39]
	v_lshl_add_u64 v[38:39], v[38:39], 0, v[176:177]
	v_mul_f32_e32 v17, v21, v54
	global_atomic_add_f32 v[38:39], v17, off
	v_add3_u32 v19, v86, v87, 42
	v_mul_hi_i32 v17, v19, s35
	v_lshrrev_b32_e32 v21, 31, v17
	v_ashrrev_i32_e32 v17, 11, v17
	v_add_u32_e32 v17, v17, v21
	v_mad_i32_i24 v19, v17, s33, v19
	v_lshlrev_b32_e32 v21, 13, v17
	v_cmp_lt_i32_e64 s[12:13], s82, v19
	v_add3_u32 v38, v21, v19, s79
	s_and_saveexec_b64 s[14:15], s[12:13]
	s_xor_b64 s[14:15], exec, s[14:15]
	s_mov_b64 s[16:17], s[92:93]
	v_add3_u32 v40, v21, v19, s79
	s_or_saveexec_b64 s[14:15], s[14:15]
	s_waitcnt lgkmcnt(0)
	v_mov_b64_e32 v[42:43], s[16:17]
	v_lshl_add_u32 v39, v17, 8, v19
	s_xor_b64 exec, exec, s[14:15]
	v_lshl_add_u32 v40, v17, 8, v19
	v_mov_b64_e32 v[42:43], s[64:65]
	s_or_b64 exec, exec, s[14:15]
	v_ashrrev_i32_e32 v41, 31, v40
	v_lshlrev_b64 v[40:41], 12, v[40:41]
	v_lshl_add_u64 v[40:41], v[42:43], 0, v[40:41]
	v_lshl_add_u64 v[40:41], v[40:41], 0, v[176:177]
	v_mul_f32_e32 v17, v22, v54
	global_atomic_add_f32 v[40:41], v17, off
	v_add3_u32 v19, v86, v87, 43
	v_mul_hi_i32 v17, v19, s35
	v_lshrrev_b32_e32 v21, 31, v17
	v_ashrrev_i32_e32 v17, 11, v17
	v_add_u32_e32 v17, v17, v21
	v_mad_i32_i24 v19, v17, s33, v19
	v_lshlrev_b32_e32 v21, 13, v17
	v_cmp_lt_i32_e64 s[14:15], s82, v19
	v_add3_u32 v22, v21, v19, s79
	s_and_saveexec_b64 s[16:17], s[14:15]
	s_xor_b64 s[16:17], exec, s[16:17]
	s_mov_b64 s[18:19], s[92:93]
	v_add3_u32 v40, v21, v19, s79
	s_or_saveexec_b64 s[16:17], s[16:17]
	s_waitcnt lgkmcnt(0)
	v_mov_b64_e32 v[42:43], s[18:19]
	v_lshl_add_u32 v58, v17, 8, v19
	s_xor_b64 exec, exec, s[16:17]
	v_lshl_add_u32 v40, v17, 8, v19
	v_mov_b64_e32 v[42:43], s[64:65]
	s_or_b64 exec, exec, s[16:17]
	v_ashrrev_i32_e32 v41, 31, v40
	v_lshlrev_b64 v[40:41], 12, v[40:41]
	v_lshl_add_u64 v[40:41], v[42:43], 0, v[40:41]
	v_lshl_add_u64 v[40:41], v[40:41], 0, v[176:177]
	v_mul_f32_e32 v17, v23, v54
	global_atomic_add_f32 v[40:41], v17, off
	v_add3_u32 v19, v86, v87, 48
	v_mul_hi_i32 v17, v19, s35
	v_lshrrev_b32_e32 v21, 31, v17
	v_ashrrev_i32_e32 v17, 11, v17
	v_add_u32_e32 v17, v17, v21
	v_mad_i32_i24 v19, v17, s33, v19
	v_lshlrev_b32_e32 v21, 13, v17
	v_cmp_lt_i32_e64 s[16:17], s82, v19
	v_add3_u32 v40, v21, v19, s79
	s_and_saveexec_b64 s[18:19], s[16:17]
	s_xor_b64 s[18:19], exec, s[18:19]
	s_mov_b64 s[20:21], s[92:93]
	v_add3_u32 v42, v21, v19, s79
	s_or_saveexec_b64 s[18:19], s[18:19]
	s_waitcnt lgkmcnt(0)
	v_mov_b64_e32 v[44:45], s[20:21]
	v_lshl_add_u32 v41, v17, 8, v19
	s_xor_b64 exec, exec, s[18:19]
	v_lshl_add_u32 v42, v17, 8, v19
	v_mov_b64_e32 v[44:45], s[64:65]
	s_or_b64 exec, exec, s[18:19]
	v_ashrrev_i32_e32 v43, 31, v42
	v_lshlrev_b64 v[42:43], 12, v[42:43]
	v_lshl_add_u64 v[42:43], v[44:45], 0, v[42:43]
	v_lshl_add_u64 v[42:43], v[42:43], 0, v[176:177]
	v_mul_f32_e32 v17, v24, v54
	global_atomic_add_f32 v[42:43], v17, off
	v_add3_u32 v19, v86, v87, 49
	v_mul_hi_i32 v17, v19, s35
	v_lshrrev_b32_e32 v21, 31, v17
	v_ashrrev_i32_e32 v17, 11, v17
	v_add_u32_e32 v17, v17, v21
	v_mad_i32_i24 v19, v17, s33, v19
	v_lshlrev_b32_e32 v21, 13, v17
	v_cmp_lt_i32_e64 s[18:19], s82, v19
	v_add3_u32 v24, v21, v19, s79
	s_and_saveexec_b64 s[20:21], s[18:19]
	s_xor_b64 s[20:21], exec, s[20:21]
	s_mov_b64 s[22:23], s[92:93]
	v_add3_u32 v42, v21, v19, s79
	s_or_saveexec_b64 s[20:21], s[20:21]
	s_waitcnt lgkmcnt(0)
	v_mov_b64_e32 v[44:45], s[22:23]
	v_lshl_add_u32 v59, v17, 8, v19
	s_xor_b64 exec, exec, s[20:21]
	v_lshl_add_u32 v42, v17, 8, v19
	v_mov_b64_e32 v[44:45], s[64:65]
	s_or_b64 exec, exec, s[20:21]
	v_ashrrev_i32_e32 v43, 31, v42
	v_lshlrev_b64 v[42:43], 12, v[42:43]
	v_lshl_add_u64 v[42:43], v[44:45], 0, v[42:43]
	v_lshl_add_u64 v[42:43], v[42:43], 0, v[176:177]
	v_mul_f32_e32 v17, v25, v54
	global_atomic_add_f32 v[42:43], v17, off
	v_add3_u32 v19, v86, v87, 50
	v_mul_hi_i32 v17, v19, s35
	v_lshrrev_b32_e32 v21, 31, v17
	v_ashrrev_i32_e32 v17, 11, v17
	v_add_u32_e32 v17, v17, v21
	v_mad_i32_i24 v19, v17, s33, v19
	v_lshlrev_b32_e32 v21, 13, v17
	v_cmp_lt_i32_e64 s[20:21], s82, v19
	v_add3_u32 v42, v21, v19, s79
	s_and_saveexec_b64 s[22:23], s[20:21]
	s_xor_b64 s[22:23], exec, s[22:23]
	s_mov_b64 s[24:25], s[92:93]
	v_add3_u32 v44, v21, v19, s79
	s_or_saveexec_b64 s[22:23], s[22:23]
	s_waitcnt lgkmcnt(0)
	v_mov_b64_e32 v[46:47], s[24:25]
	v_lshl_add_u32 v43, v17, 8, v19
	s_xor_b64 exec, exec, s[22:23]
	v_lshl_add_u32 v44, v17, 8, v19
	v_mov_b64_e32 v[46:47], s[64:65]
	s_or_b64 exec, exec, s[22:23]
	v_ashrrev_i32_e32 v45, 31, v44
	v_lshlrev_b64 v[44:45], 12, v[44:45]
	v_lshl_add_u64 v[44:45], v[46:47], 0, v[44:45]
	v_lshl_add_u64 v[44:45], v[44:45], 0, v[176:177]
	v_mul_f32_e32 v17, v26, v54
	global_atomic_add_f32 v[44:45], v17, off
	v_add3_u32 v19, v86, v87, 51
	v_mul_hi_i32 v17, v19, s35
	v_lshrrev_b32_e32 v21, 31, v17
	v_ashrrev_i32_e32 v17, 11, v17
	v_add_u32_e32 v17, v17, v21
	v_mad_i32_i24 v19, v17, s33, v19
	v_lshlrev_b32_e32 v21, 13, v17
	v_cmp_lt_i32_e64 s[22:23], s82, v19
	v_add3_u32 v26, v21, v19, s79
	s_and_saveexec_b64 s[24:25], s[22:23]
	s_xor_b64 s[24:25], exec, s[24:25]
	s_mov_b64 s[26:27], s[92:93]
	v_add3_u32 v44, v21, v19, s79
	s_or_saveexec_b64 s[24:25], s[24:25]
	s_waitcnt lgkmcnt(0)
	v_mov_b64_e32 v[46:47], s[26:27]
	v_lshl_add_u32 v60, v17, 8, v19
	s_xor_b64 exec, exec, s[24:25]
	v_lshl_add_u32 v44, v17, 8, v19
	v_mov_b64_e32 v[46:47], s[64:65]
	s_or_b64 exec, exec, s[24:25]
	v_ashrrev_i32_e32 v45, 31, v44
	v_lshlrev_b64 v[44:45], 12, v[44:45]
	v_lshl_add_u64 v[44:45], v[46:47], 0, v[44:45]
	v_lshl_add_u64 v[44:45], v[44:45], 0, v[176:177]
	v_mul_f32_e32 v17, v27, v54
	global_atomic_add_f32 v[44:45], v17, off
	v_add3_u32 v19, v86, v87, 56
	v_mul_hi_i32 v17, v19, s35
	v_lshrrev_b32_e32 v21, 31, v17
	v_ashrrev_i32_e32 v17, 11, v17
	v_add_u32_e32 v17, v17, v21
	v_mad_i32_i24 v19, v17, s33, v19
	v_lshlrev_b32_e32 v21, 13, v17
	v_cmp_lt_i32_e64 s[24:25], s82, v19
	v_add3_u32 v44, v21, v19, s79
	s_and_saveexec_b64 s[26:27], s[24:25]
	s_xor_b64 s[26:27], exec, s[26:27]
	s_mov_b64 s[28:29], s[92:93]
	v_add3_u32 v46, v21, v19, s79
	s_or_saveexec_b64 s[26:27], s[26:27]
	s_waitcnt lgkmcnt(0)
	v_mov_b64_e32 v[50:51], s[28:29]
	v_lshl_add_u32 v45, v17, 8, v19
	s_xor_b64 exec, exec, s[26:27]
	v_lshl_add_u32 v46, v17, 8, v19
	v_mov_b64_e32 v[50:51], s[64:65]
	s_or_b64 exec, exec, s[26:27]
	v_ashrrev_i32_e32 v47, 31, v46
	v_lshlrev_b64 v[46:47], 12, v[46:47]
	v_lshl_add_u64 v[46:47], v[50:51], 0, v[46:47]
	v_lshl_add_u64 v[46:47], v[46:47], 0, v[176:177]
	v_mul_f32_e32 v17, v28, v54
	global_atomic_add_f32 v[46:47], v17, off
	v_add3_u32 v19, v86, v87, 57
	v_mul_hi_i32 v17, v19, s35
	v_lshrrev_b32_e32 v21, 31, v17
	v_ashrrev_i32_e32 v17, 11, v17
	v_add_u32_e32 v17, v17, v21
	v_mad_i32_i24 v19, v17, s33, v19
	v_lshlrev_b32_e32 v21, 13, v17
	v_cmp_lt_i32_e64 s[26:27], s82, v19
	v_add3_u32 v28, v21, v19, s79
	s_and_saveexec_b64 s[28:29], s[26:27]
	s_xor_b64 s[28:29], exec, s[28:29]
	s_mov_b64 s[30:31], s[92:93]
	v_add3_u32 v46, v21, v19, s79
	s_or_saveexec_b64 s[28:29], s[28:29]
	s_waitcnt lgkmcnt(0)
	v_mov_b64_e32 v[50:51], s[30:31]
	v_lshl_add_u32 v61, v17, 8, v19
	s_xor_b64 exec, exec, s[28:29]
	v_lshl_add_u32 v46, v17, 8, v19
	v_mov_b64_e32 v[50:51], s[64:65]
	s_or_b64 exec, exec, s[28:29]
	v_ashrrev_i32_e32 v47, 31, v46
	v_lshlrev_b64 v[46:47], 12, v[46:47]
	v_lshl_add_u64 v[46:47], v[50:51], 0, v[46:47]
	v_lshl_add_u64 v[46:47], v[46:47], 0, v[176:177]
	v_mul_f32_e32 v17, v29, v54
	global_atomic_add_f32 v[46:47], v17, off
	v_add3_u32 v19, v86, v87, 58
	v_mul_hi_i32 v17, v19, s35
	v_lshrrev_b32_e32 v21, 31, v17
	v_ashrrev_i32_e32 v17, 11, v17
	v_add_u32_e32 v17, v17, v21
	v_mad_i32_i24 v19, v17, s33, v19
	v_lshlrev_b32_e32 v21, 13, v17
	v_cmp_lt_i32_e64 s[28:29], s82, v19
	v_add3_u32 v46, v21, v19, s79
	s_and_saveexec_b64 s[30:31], s[28:29]
	s_xor_b64 s[30:31], exec, s[30:31]
	s_mov_b64 s[74:75], s[92:93]
	v_add3_u32 v50, v21, v19, s79
	s_or_saveexec_b64 s[30:31], s[30:31]
	s_waitcnt lgkmcnt(0)
	v_mov_b64_e32 v[52:53], s[74:75]
	v_lshl_add_u32 v47, v17, 8, v19
	s_xor_b64 exec, exec, s[30:31]
	v_lshl_add_u32 v50, v17, 8, v19
	v_mov_b64_e32 v[52:53], s[64:65]
	s_or_b64 exec, exec, s[30:31]
	v_ashrrev_i32_e32 v51, 31, v50
	v_lshlrev_b64 v[50:51], 12, v[50:51]
	v_lshl_add_u64 v[50:51], v[52:53], 0, v[50:51]
	v_lshl_add_u64 v[50:51], v[50:51], 0, v[176:177]
	v_mul_f32_e32 v17, v30, v54
	global_atomic_add_f32 v[50:51], v17, off
	v_add3_u32 v19, v86, v87, 59
	v_mul_hi_i32 v17, v19, s35
	v_lshrrev_b32_e32 v21, 31, v17
	v_ashrrev_i32_e32 v17, 11, v17
	v_add_u32_e32 v17, v17, v21
	v_mad_i32_i24 v19, v17, s33, v19
	v_lshlrev_b32_e32 v21, 13, v17
	v_cmp_lt_i32_e64 s[30:31], s82, v19
	v_add3_u32 v30, v21, v19, s79
	s_and_saveexec_b64 s[74:75], s[30:31]
	s_xor_b64 s[74:75], exec, s[74:75]
	s_mov_b64 s[76:77], s[92:93]
	v_add3_u32 v50, v21, v19, s79
	s_or_saveexec_b64 s[74:75], s[74:75]
	s_waitcnt lgkmcnt(0)
	v_mov_b64_e32 v[52:53], s[76:77]
	v_lshl_add_u32 v62, v17, 8, v19
	s_xor_b64 exec, exec, s[74:75]
	v_lshl_add_u32 v50, v17, 8, v19
	v_mov_b64_e32 v[52:53], s[64:65]
	s_or_b64 exec, exec, s[74:75]
	v_ashrrev_i32_e32 v51, 31, v50
	v_lshlrev_b64 v[50:51], 12, v[50:51]
	v_lshl_add_u64 v[50:51], v[52:53], 0, v[50:51]
	v_mov_b32_e32 v49, v177
	v_lshl_add_u64 v[50:51], v[50:51], 0, v[176:177]
	v_mul_f32_e32 v17, v31, v54
	v_lshl_add_u64 v[48:49], s[58:59], 0, v[48:49]
	global_atomic_add_f32 v[50:51], v17, off
	global_load_dword v50, v[48:49], off
	s_and_saveexec_b64 s[74:75], vcc
	s_xor_b64 s[74:75], exec, s[74:75]
	s_mov_b64 s[76:77], s[92:93]
	s_or_saveexec_b64 s[74:75], s[74:75]
	s_waitcnt lgkmcnt(0)
	v_mov_b64_e32 v[48:49], s[76:77]
	s_xor_b64 exec, exec, s[74:75]
	v_mov_b64_e32 v[48:49], s[64:65]
	v_mov_b32_e32 v32, v33
	s_or_b64 exec, exec, s[74:75]
	v_ashrrev_i32_e32 v33, 31, v32
	v_lshlrev_b64 v[32:33], 12, v[32:33]
	v_lshl_add_u64 v[32:33], v[48:49], 0, v[32:33]
	v_lshl_add_u64 v[32:33], v[32:33], 0, v[176:177]
	s_waitcnt vmcnt(0)
	v_mul_f32_e32 v0, v0, v50
	global_atomic_add_f32 v[32:33], v0, off offset:128
	s_and_saveexec_b64 s[76:77], s[2:3]
	s_xor_b64 s[2:3], exec, s[76:77]
	s_mov_b64 s[74:75], s[92:93]
	s_or_saveexec_b64 s[2:3], s[2:3]
	s_waitcnt lgkmcnt(0)
	v_mov_b64_e32 v[32:33], s[74:75]
	s_xor_b64 exec, exec, s[2:3]
	v_mov_b64_e32 v[32:33], s[64:65]
	v_mov_b32_e32 v16, v55
	s_or_b64 exec, exec, s[2:3]
	v_ashrrev_i32_e32 v17, 31, v16
	v_lshlrev_b64 v[16:17], 12, v[16:17]
	v_lshl_add_u64 v[16:17], v[32:33], 0, v[16:17]
	v_lshl_add_u64 v[16:17], v[16:17], 0, v[176:177]
	v_mul_f32_e32 v0, v1, v50
	global_atomic_add_f32 v[16:17], v0, off offset:128
	s_and_saveexec_b64 s[2:3], s[4:5]
	s_xor_b64 s[2:3], exec, s[2:3]
	s_mov_b64 s[74:75], s[92:93]
	s_or_saveexec_b64 s[2:3], s[2:3]
	s_waitcnt lgkmcnt(0)
	v_mov_b64_e32 v[0:1], s[74:75]
	s_xor_b64 exec, exec, s[2:3]
	v_mov_b64_e32 v[0:1], s[64:65]
	v_mov_b32_e32 v34, v35
	s_or_b64 exec, exec, s[2:3]
	v_ashrrev_i32_e32 v35, 31, v34
	v_lshlrev_b64 v[16:17], 12, v[34:35]
	v_lshl_add_u64 v[0:1], v[0:1], 0, v[16:17]
	v_lshl_add_u64 v[0:1], v[0:1], 0, v[176:177]
	v_mul_f32_e32 v2, v2, v50
	global_atomic_add_f32 v[0:1], v2, off offset:128
	s_and_saveexec_b64 s[2:3], s[6:7]
	s_xor_b64 s[2:3], exec, s[2:3]
	s_mov_b64 s[4:5], s[92:93]
	s_or_saveexec_b64 s[2:3], s[2:3]
	s_waitcnt lgkmcnt(0)
	v_mov_b64_e32 v[0:1], s[4:5]
	s_xor_b64 exec, exec, s[2:3]
	v_mov_b64_e32 v[0:1], s[64:65]
	v_mov_b32_e32 v18, v56
	s_or_b64 exec, exec, s[2:3]
	v_ashrrev_i32_e32 v19, 31, v18
	v_lshlrev_b64 v[16:17], 12, v[18:19]
	v_lshl_add_u64 v[0:1], v[0:1], 0, v[16:17]
	v_lshl_add_u64 v[0:1], v[0:1], 0, v[176:177]
	v_mul_f32_e32 v2, v3, v50
	global_atomic_add_f32 v[0:1], v2, off offset:128
	s_and_saveexec_b64 s[2:3], s[8:9]
	s_xor_b64 s[2:3], exec, s[2:3]
	s_mov_b64 s[4:5], s[92:93]
	s_or_saveexec_b64 s[2:3], s[2:3]
	s_waitcnt lgkmcnt(0)
	v_mov_b64_e32 v[0:1], s[4:5]
	s_xor_b64 exec, exec, s[2:3]
	v_mov_b64_e32 v[0:1], s[64:65]
	v_mov_b32_e32 v36, v37
	s_or_b64 exec, exec, s[2:3]
	v_ashrrev_i32_e32 v37, 31, v36
	v_lshlrev_b64 v[2:3], 12, v[36:37]
	v_lshl_add_u64 v[0:1], v[0:1], 0, v[2:3]
	v_lshl_add_u64 v[0:1], v[0:1], 0, v[176:177]
	v_mul_f32_e32 v2, v4, v50
	global_atomic_add_f32 v[0:1], v2, off offset:128
	s_and_saveexec_b64 s[2:3], s[10:11]
	s_xor_b64 s[2:3], exec, s[2:3]
	s_mov_b64 s[4:5], s[92:93]
	s_or_saveexec_b64 s[2:3], s[2:3]
	s_waitcnt lgkmcnt(0)
	v_mov_b64_e32 v[0:1], s[4:5]
	s_xor_b64 exec, exec, s[2:3]
	v_mov_b64_e32 v[0:1], s[64:65]
	v_mov_b32_e32 v20, v57
	s_or_b64 exec, exec, s[2:3]
	v_ashrrev_i32_e32 v21, 31, v20
	v_lshlrev_b64 v[2:3], 12, v[20:21]
	v_lshl_add_u64 v[0:1], v[0:1], 0, v[2:3]
	v_lshl_add_u64 v[0:1], v[0:1], 0, v[176:177]
	v_mul_f32_e32 v2, v5, v50
	global_atomic_add_f32 v[0:1], v2, off offset:128
	s_and_saveexec_b64 s[2:3], s[12:13]
	s_xor_b64 s[2:3], exec, s[2:3]
	s_mov_b64 s[4:5], s[92:93]
	s_or_saveexec_b64 s[2:3], s[2:3]
	s_waitcnt lgkmcnt(0)
	v_mov_b64_e32 v[0:1], s[4:5]
	s_xor_b64 exec, exec, s[2:3]
	v_mov_b64_e32 v[0:1], s[64:65]
	v_mov_b32_e32 v38, v39
	s_or_b64 exec, exec, s[2:3]
	v_ashrrev_i32_e32 v39, 31, v38
	v_lshlrev_b64 v[2:3], 12, v[38:39]
	v_lshl_add_u64 v[0:1], v[0:1], 0, v[2:3]
	v_lshl_add_u64 v[0:1], v[0:1], 0, v[176:177]
	v_mul_f32_e32 v2, v6, v50
	global_atomic_add_f32 v[0:1], v2, off offset:128
	s_and_saveexec_b64 s[2:3], s[14:15]
	s_xor_b64 s[2:3], exec, s[2:3]
	s_mov_b64 s[4:5], s[92:93]
	s_or_saveexec_b64 s[2:3], s[2:3]
	s_waitcnt lgkmcnt(0)
	v_mov_b64_e32 v[0:1], s[4:5]
	s_xor_b64 exec, exec, s[2:3]
	v_mov_b64_e32 v[0:1], s[64:65]
	v_mov_b32_e32 v22, v58
	s_or_b64 exec, exec, s[2:3]
	v_ashrrev_i32_e32 v23, 31, v22
	v_lshlrev_b64 v[2:3], 12, v[22:23]
	v_lshl_add_u64 v[0:1], v[0:1], 0, v[2:3]
	v_lshl_add_u64 v[0:1], v[0:1], 0, v[176:177]
	v_mul_f32_e32 v2, v7, v50
	global_atomic_add_f32 v[0:1], v2, off offset:128
	s_and_saveexec_b64 s[2:3], s[16:17]
	s_xor_b64 s[2:3], exec, s[2:3]
	s_mov_b64 s[4:5], s[92:93]
	s_or_saveexec_b64 s[2:3], s[2:3]
	s_waitcnt lgkmcnt(0)
	v_mov_b64_e32 v[0:1], s[4:5]
	s_xor_b64 exec, exec, s[2:3]
	v_mov_b64_e32 v[0:1], s[64:65]
	v_mov_b32_e32 v40, v41
	s_or_b64 exec, exec, s[2:3]
	v_ashrrev_i32_e32 v41, 31, v40
	v_lshlrev_b64 v[2:3], 12, v[40:41]
	v_lshl_add_u64 v[0:1], v[0:1], 0, v[2:3]
	v_lshl_add_u64 v[0:1], v[0:1], 0, v[176:177]
	v_mul_f32_e32 v2, v8, v50
	global_atomic_add_f32 v[0:1], v2, off offset:128
	s_and_saveexec_b64 s[2:3], s[18:19]
	s_xor_b64 s[2:3], exec, s[2:3]
	s_mov_b64 s[4:5], s[92:93]
	s_or_saveexec_b64 s[2:3], s[2:3]
	s_waitcnt lgkmcnt(0)
	v_mov_b64_e32 v[0:1], s[4:5]
	s_xor_b64 exec, exec, s[2:3]
	v_mov_b64_e32 v[0:1], s[64:65]
	v_mov_b32_e32 v24, v59
	s_or_b64 exec, exec, s[2:3]
	v_ashrrev_i32_e32 v25, 31, v24
	v_lshlrev_b64 v[2:3], 12, v[24:25]
	v_lshl_add_u64 v[0:1], v[0:1], 0, v[2:3]
	v_lshl_add_u64 v[0:1], v[0:1], 0, v[176:177]
	v_mul_f32_e32 v2, v9, v50
	global_atomic_add_f32 v[0:1], v2, off offset:128
	s_and_saveexec_b64 s[2:3], s[20:21]
	s_xor_b64 s[2:3], exec, s[2:3]
	s_mov_b64 s[4:5], s[92:93]
	s_or_saveexec_b64 s[2:3], s[2:3]
	s_waitcnt lgkmcnt(0)
	v_mov_b64_e32 v[0:1], s[4:5]
	s_xor_b64 exec, exec, s[2:3]
	v_mov_b64_e32 v[0:1], s[64:65]
	v_mov_b32_e32 v42, v43
	s_or_b64 exec, exec, s[2:3]
	v_ashrrev_i32_e32 v43, 31, v42
	v_lshlrev_b64 v[2:3], 12, v[42:43]
	v_lshl_add_u64 v[0:1], v[0:1], 0, v[2:3]
	v_lshl_add_u64 v[0:1], v[0:1], 0, v[176:177]
	v_mul_f32_e32 v2, v10, v50
	global_atomic_add_f32 v[0:1], v2, off offset:128
	s_and_saveexec_b64 s[2:3], s[22:23]
	s_xor_b64 s[2:3], exec, s[2:3]
	s_mov_b64 s[4:5], s[92:93]
	s_or_saveexec_b64 s[2:3], s[2:3]
	s_waitcnt lgkmcnt(0)
	v_mov_b64_e32 v[0:1], s[4:5]
	s_xor_b64 exec, exec, s[2:3]
	v_mov_b64_e32 v[0:1], s[64:65]
	v_mov_b32_e32 v26, v60
	s_or_b64 exec, exec, s[2:3]
	v_ashrrev_i32_e32 v27, 31, v26
	v_lshlrev_b64 v[2:3], 12, v[26:27]
	v_lshl_add_u64 v[0:1], v[0:1], 0, v[2:3]
	v_lshl_add_u64 v[0:1], v[0:1], 0, v[176:177]
	v_mul_f32_e32 v2, v11, v50
	global_atomic_add_f32 v[0:1], v2, off offset:128
	s_and_saveexec_b64 s[2:3], s[24:25]
	s_xor_b64 s[2:3], exec, s[2:3]
	s_mov_b64 s[4:5], s[92:93]
	s_or_saveexec_b64 s[2:3], s[2:3]
	s_waitcnt lgkmcnt(0)
	v_mov_b64_e32 v[0:1], s[4:5]
	s_xor_b64 exec, exec, s[2:3]
	v_mov_b64_e32 v[0:1], s[64:65]
	v_mov_b32_e32 v44, v45
	s_or_b64 exec, exec, s[2:3]
	v_ashrrev_i32_e32 v45, 31, v44
	v_lshlrev_b64 v[2:3], 12, v[44:45]
	v_lshl_add_u64 v[0:1], v[0:1], 0, v[2:3]
	v_lshl_add_u64 v[0:1], v[0:1], 0, v[176:177]
	v_mul_f32_e32 v2, v12, v50
	global_atomic_add_f32 v[0:1], v2, off offset:128
	s_and_saveexec_b64 s[2:3], s[26:27]
	s_xor_b64 s[2:3], exec, s[2:3]
	s_mov_b64 s[4:5], s[92:93]
	s_or_saveexec_b64 s[2:3], s[2:3]
	s_waitcnt lgkmcnt(0)
	v_mov_b64_e32 v[0:1], s[4:5]
	s_xor_b64 exec, exec, s[2:3]
	v_mov_b64_e32 v[0:1], s[64:65]
	v_mov_b32_e32 v28, v61
	s_or_b64 exec, exec, s[2:3]
	v_ashrrev_i32_e32 v29, 31, v28
	v_lshlrev_b64 v[2:3], 12, v[28:29]
	v_lshl_add_u64 v[0:1], v[0:1], 0, v[2:3]
	v_lshl_add_u64 v[0:1], v[0:1], 0, v[176:177]
	v_mul_f32_e32 v2, v13, v50
	global_atomic_add_f32 v[0:1], v2, off offset:128
	s_and_saveexec_b64 s[2:3], s[28:29]
	s_xor_b64 s[2:3], exec, s[2:3]
	s_mov_b64 s[4:5], s[92:93]
	s_or_saveexec_b64 s[2:3], s[2:3]
	s_waitcnt lgkmcnt(0)
	v_mov_b64_e32 v[0:1], s[4:5]
	s_xor_b64 exec, exec, s[2:3]
	v_mov_b64_e32 v[0:1], s[64:65]
	v_mov_b32_e32 v46, v47
	s_or_b64 exec, exec, s[2:3]
	v_ashrrev_i32_e32 v47, 31, v46
	v_lshlrev_b64 v[2:3], 12, v[46:47]
	v_lshl_add_u64 v[0:1], v[0:1], 0, v[2:3]
	v_lshl_add_u64 v[0:1], v[0:1], 0, v[176:177]
	v_mul_f32_e32 v2, v14, v50
	global_atomic_add_f32 v[0:1], v2, off offset:128
	s_and_saveexec_b64 s[2:3], s[30:31]
	s_xor_b64 s[2:3], exec, s[2:3]
	s_mov_b64 s[4:5], s[92:93]
	s_or_saveexec_b64 s[2:3], s[2:3]
	s_waitcnt lgkmcnt(0)
	v_mov_b64_e32 v[0:1], s[4:5]
	s_xor_b64 exec, exec, s[2:3]
	s_cbranch_execz .LBB0_1171
	v_mov_b64_e32 v[0:1], s[64:65]
	v_mov_b32_e32 v30, v62
	s_branch .LBB0_1171
